# u2 + snake MFMA order in all four K-loops (consecutive MFMAs always share one source fragment)
# baseline (speedup 1.0000x reference)
; #define PG8_STAGE(bufoff, gbase, voff) do { _Pragma("unroll") for (int _i = 0; _i < 2; ++_i) \
;         __builtin_amdgcn_global_load_lds((const unsigned*)((const char*)(gbase) + (voff)[_i]), (PG8_LAS unsigned*)(lds + (bufoff) + ldsw + _i * 8192), 16, 0, 0); } while (0)
; #define PG8_LDA(dst, b, h) do { _Pragma("unroll") for (int m = 0; m < 4; ++m) _Pragma("unroll") for (int k = 0; k < 2; ++k) dst[m][k] = *(const PG8_LAS bf16x8*)(lds + PG8_SA(b, h) + aoff + m * 2048 + k * 1024); } while (0)
; #define PG8_LDB(dst, b, h) do { _Pragma("unroll") for (int n = 0; n < 2; ++n) _Pragma("unroll") for (int k = 0; k < 2; ++k) dst[n][k] = *(const PG8_LAS bf16x8*)(lds + PG8_SB(b, h) + boff + n * 2048 + k * 1024); } while (0)
; #define PG8_MMA(ai, bj, At, Bt) do { __builtin_amdgcn_s_setprio(1); _Pragma("unroll") for (int m = 0; m < 4; ++m) _Pragma("unroll") for (int n = 0; n < 2; ++n) _Pragma("unroll") for (int k = 0; k < 2; ++k) \
;         acc[ai][bj][m][n] = __builtin_amdgcn_mfma_f32_16x16x32_bf16(Bt[n][k], At[m][k], acc[ai][bj][m][n], 0, 0, 0); __builtin_amdgcn_s_setprio(0); } while (0)
; #define PG8_WAIT_V(n) asm volatile("s_waitcnt vmcnt(" #n ")" ::: "memory")
; #define PG8_WAIT_L(n) asm volatile("s_waitcnt lgkmcnt(" #n ")" ::: "memory")
; template <class Epi, class Sched, bool ALIGN_EPI = false, bool SP2 = false>
; __device__ __forceinline__ void gemm_phase(PG8_LAS unsigned char* lds, const Gemm g, const Sched& S, const Epi& E, int tid_in) {
;     ...
;             const bool last = (t == nt - 2);
;             const char* a1 = cA + (size_t)(t + 1) * kstep;
;             const char* a2 = last ? nA : cA + (size_t)(t + 2) * kstep; const char* b2 = last ? nB : cB + (size_t)(t + 2) * kstep;
;             const char* a3 = a2 + kstep; const char* b3 = b2 + kstep;
;             if (last && has_next) S.a_ready(nxt);
;             if constexpr (SP2) {
;             PG8_LDB(B0, 0, 0); PG8_LDB(B1, 0, 1); PG8_SCHED; PG8_LDA(At, 0, 0); PG8_STAGE(PG8_SA(1, 1), a1 + hstep, voffA);
;             PG8_WAIT_V(8); PG8_WAIT_L(0); PG8_BAR; PG8_MMA(0, 0, At, B0); PG8_MMA(0, 1, At, B1); PG8_BAR; PG8_SCHED;
;             PG8_LDA(At, 0, 1); PG8_STAGE(PG8_SB(0, 0), b2, voffB); PG8_STAGE(PG8_SB(0, 1), b2 + hstep, voffB); PG8_STAGE(PG8_SA(0, 0), a2, voffA);
;             PG8_WAIT_V(8); PG8_WAIT_L(0); PG8_BAR; PG8_MMA(1, 0, At, B0); PG8_MMA(1, 1, At, B1); PG8_BAR; PG8_SCHED;
.LBB0_125:
	s_add_u32 s24, s6, 0xfff80080
	s_addc_u32 s25, s7, -1
	s_add_i32 s96, 0, 0x10000
	s_cmp_eq_u32 s95, 28
	s_cselect_b32 s75, s63, s25
	s_cselect_b32 s74, s71, s24
	s_cselect_b32 s73, s61, s90
	s_cselect_b32 s72, s85, s87
	s_add_i32 s24, 0, 0x14000
	v_add_u32_e32 v154, s96, v165
	v_add_u32_e32 v162, s24, v165
	ds_read_b128 v[142:145], v154
	ds_read_b128 v[146:149], v154 offset:1024
	ds_read_b128 v[150:153], v154 offset:2048
	ds_read_b128 v[154:157], v154 offset:3072
	ds_read_b128 v[158:161], v162
	ds_read_b128 v[170:173], v162 offset:1024
	ds_read_b128 v[174:177], v162 offset:2048
	ds_read_b128 v[178:181], v162 offset:3072
	v_lshl_add_u64 v[162:163], s[6:7], 0, v[138:139]
	s_add_i32 m0, s16, 0xc000
	ds_read_b128 v[182:185], v169
	ds_read_b128 v[186:189], v169 offset:1024
	ds_read_b128 v[190:193], v169 offset:2048
	ds_read_b128 v[194:197], v169 offset:3072
	ds_read_b128 v[198:201], v169 offset:4096
	ds_read_b128 v[202:205], v169 offset:5120
	ds_read_b128 v[206:209], v169 offset:6144
	ds_read_b128 v[210:213], v169 offset:7168
	global_load_lds_dwordx4 v[162:163], off
	v_lshl_add_u64 v[162:163], s[6:7], 0, v[140:141]
	s_add_i32 m0, s16, 0xe000
	s_nop 0
	global_load_lds_dwordx4 v[162:163], off
	s_waitcnt vmcnt(8)
	s_waitcnt lgkmcnt(0)
	s_setprio 1
	s_barrier
	v_mfma_f32_16x16x32_bf16 v[126:129], v[142:145], v[182:185], v[126:129]
	v_mfma_f32_16x16x32_bf16 v[122:125], v[150:153], v[182:185], v[122:125]
	v_mfma_f32_16x16x32_bf16 v[106:109], v[150:153], v[190:193], v[106:109]
	v_mfma_f32_16x16x32_bf16 v[110:113], v[142:145], v[190:193], v[110:113]
	v_mfma_f32_16x16x32_bf16 v[94:97], v[142:145], v[198:201], v[94:97]
	v_mfma_f32_16x16x32_bf16 v[90:93], v[150:153], v[198:201], v[90:93]
	v_mfma_f32_16x16x32_bf16 v[74:77], v[150:153], v[206:209], v[74:77]
	v_mfma_f32_16x16x32_bf16 v[78:81], v[142:145], v[206:209], v[78:81]
	v_mfma_f32_16x16x32_bf16 v[126:129], v[146:149], v[186:189], v[126:129]
	v_mfma_f32_16x16x32_bf16 v[122:125], v[154:157], v[186:189], v[122:125]
	v_mfma_f32_16x16x32_bf16 v[106:109], v[154:157], v[194:197], v[106:109]
	v_mfma_f32_16x16x32_bf16 v[110:113], v[146:149], v[194:197], v[110:113]
	v_mfma_f32_16x16x32_bf16 v[94:97], v[146:149], v[202:205], v[94:97]
	v_mfma_f32_16x16x32_bf16 v[90:93], v[154:157], v[202:205], v[90:93]
	v_mfma_f32_16x16x32_bf16 v[74:77], v[154:157], v[210:213], v[74:77]
	v_mfma_f32_16x16x32_bf16 v[78:81], v[146:149], v[210:213], v[78:81]
	v_mfma_f32_16x16x32_bf16 v[118:121], v[158:161], v[182:185], v[118:121]
	v_mfma_f32_16x16x32_bf16 v[114:117], v[174:177], v[182:185], v[114:117]
	v_mfma_f32_16x16x32_bf16 v[98:101], v[174:177], v[190:193], v[98:101]
	v_mfma_f32_16x16x32_bf16 v[102:105], v[158:161], v[190:193], v[102:105]
	v_mfma_f32_16x16x32_bf16 v[86:89], v[158:161], v[198:201], v[86:89]
	v_mfma_f32_16x16x32_bf16 v[82:85], v[174:177], v[198:201], v[82:85]
	v_mfma_f32_16x16x32_bf16 v[66:69], v[174:177], v[206:209], v[66:69]
	v_mfma_f32_16x16x32_bf16 v[70:73], v[158:161], v[206:209], v[70:73]
	v_mfma_f32_16x16x32_bf16 v[118:121], v[170:173], v[186:189], v[118:121]
	v_mfma_f32_16x16x32_bf16 v[114:117], v[178:181], v[186:189], v[114:117]
	v_mfma_f32_16x16x32_bf16 v[98:101], v[178:181], v[194:197], v[98:101]
	v_mfma_f32_16x16x32_bf16 v[102:105], v[170:173], v[194:197], v[102:105]
	v_mfma_f32_16x16x32_bf16 v[86:89], v[170:173], v[202:205], v[86:89]
	v_mfma_f32_16x16x32_bf16 v[82:85], v[178:181], v[202:205], v[82:85]
	v_mfma_f32_16x16x32_bf16 v[66:69], v[178:181], v[210:213], v[66:69]
	v_mfma_f32_16x16x32_bf16 v[70:73], v[170:173], v[210:213], v[70:73]
	s_barrier
	s_setprio 0
	s_add_i32 s25, s96, s15
	v_lshl_add_u64 v[162:163], s[72:73], 0, v[132:133]
	s_mov_b32 m0, s25
	ds_read_b128 v[182:185], v169 offset:16384
	ds_read_b128 v[186:189], v169 offset:17408
	ds_read_b128 v[190:193], v169 offset:18432
	ds_read_b128 v[194:197], v169 offset:19456
	ds_read_b128 v[198:201], v169 offset:20480
	ds_read_b128 v[202:205], v169 offset:21504
	ds_read_b128 v[206:209], v169 offset:22528
	ds_read_b128 v[210:213], v169 offset:23552
	global_load_lds_dwordx4 v[162:163], off
	s_add_i32 m0, s25, 0x2000
	s_add_u32 s96, s72, 0x80000
	v_lshl_add_u64 v[166:167], s[72:73], 0, v[136:137]
	s_addc_u32 s97, s73, 0
	s_add_i32 s24, s24, s15
	global_load_lds_dwordx4 v[166:167], off
	v_lshl_add_u64 v[218:219], s[96:97], 0, v[132:133]
	s_mov_b32 m0, s24
	v_lshl_add_u64 v[220:221], s[74:75], 0, v[134:135]
	global_load_lds_dwordx4 v[218:219], off
	v_lshl_add_u64 v[218:219], s[96:97], 0, v[136:137]
	s_add_i32 m0, s24, 0x2000
	s_nop 0
	global_load_lds_dwordx4 v[218:219], off
	v_lshl_add_u64 v[218:219], s[74:75], 0, v[130:131]
	s_mov_b32 m0, s16
	s_nop 0
	global_load_lds_dwordx4 v[218:219], off
	s_mov_b32 m0, s26
	s_nop 0
	global_load_lds_dwordx4 v[220:221], off
	s_waitcnt vmcnt(8)
	s_waitcnt lgkmcnt(0)
	s_setprio 1
	s_barrier
; #define PG8_STAGE(bufoff, gbase, voff) do { _Pragma("unroll") for (int _i = 0; _i < 2; ++_i) \
;         __builtin_amdgcn_global_load_lds((const unsigned*)((const char*)(gbase) + (voff)[_i]), (PG8_LAS unsigned*)(lds + (bufoff) + ldsw + _i * 8192), 16, 0, 0); } while (0)
; #define PG8_LDA(dst, b, h) do { _Pragma("unroll") for (int m = 0; m < 4; ++m) _Pragma("unroll") for (int k = 0; k < 2; ++k) dst[m][k] = *(const PG8_LAS bf16x8*)(lds + PG8_SA(b, h) + aoff + m * 2048 + k * 1024); } while (0)
; #define PG8_LDB(dst, b, h) do { _Pragma("unroll") for (int n = 0; n < 2; ++n) _Pragma("unroll") for (int k = 0; k < 2; ++k) dst[n][k] = *(const PG8_LAS bf16x8*)(lds + PG8_SB(b, h) + boff + n * 2048 + k * 1024); } while (0)
; #define PG8_MMA(ai, bj, At, Bt) do { __builtin_amdgcn_s_setprio(1); _Pragma("unroll") for (int m = 0; m < 4; ++m) _Pragma("unroll") for (int n = 0; n < 2; ++n) _Pragma("unroll") for (int k = 0; k < 2; ++k) \
;         acc[ai][bj][m][n] = __builtin_amdgcn_mfma_f32_16x16x32_bf16(Bt[n][k], At[m][k], acc[ai][bj][m][n], 0, 0, 0); __builtin_amdgcn_s_setprio(0); } while (0)
; #define PG8_WAIT_V(n) asm volatile("s_waitcnt vmcnt(" #n ")" ::: "memory")
; #define PG8_WAIT_L(n) asm volatile("s_waitcnt lgkmcnt(" #n ")" ::: "memory")
; #define PG8_BAR __builtin_amdgcn_s_barrier()
; #define PG8_SCHED __builtin_amdgcn_sched_barrier(0)
; template <class Epi, class Sched, bool ALIGN_EPI = false, bool SP2 = false>
; __device__ __forceinline__ void gemm_phase(PG8_LAS unsigned char* lds, const Gemm g, const Sched& S, const Epi& E, int tid_in) {
;     ...
;             PG8_WAIT_V(8); PG8_WAIT_L(0); PG8_BAR; PG8_MMA(1, 0, At, B0); PG8_MMA(1, 1, At, B1); PG8_BAR; PG8_SCHED;
;             PG8_LDB(B0, 1, 0); PG8_LDB(B1, 1, 1); PG8_SCHED; PG8_LDA(At, 1, 0); PG8_STAGE(PG8_SA(0, 1), a2 + hstep, voffA);
;             PG8_WAIT_V(8); PG8_WAIT_L(0); PG8_BAR; PG8_MMA(0, 0, At, B0); PG8_MMA(0, 1, At, B1); PG8_BAR; PG8_SCHED;
	v_mfma_f32_16x16x32_bf16 v[62:65], v[142:145], v[182:185], v[62:65]
	v_mfma_f32_16x16x32_bf16 v[58:61], v[150:153], v[182:185], v[58:61]
	v_mfma_f32_16x16x32_bf16 v[42:45], v[150:153], v[190:193], v[42:45]
	v_mfma_f32_16x16x32_bf16 v[46:49], v[142:145], v[190:193], v[46:49]
	v_mfma_f32_16x16x32_bf16 v[30:33], v[142:145], v[198:201], v[30:33]
	v_mfma_f32_16x16x32_bf16 v[26:29], v[150:153], v[198:201], v[26:29]
	v_mfma_f32_16x16x32_bf16 v[8:11], v[150:153], v[206:209], v[8:11]
	v_mfma_f32_16x16x32_bf16 v[12:15], v[142:145], v[206:209], v[12:15]
	v_mfma_f32_16x16x32_bf16 v[62:65], v[146:149], v[186:189], v[62:65]
	v_mfma_f32_16x16x32_bf16 v[58:61], v[154:157], v[186:189], v[58:61]
	v_mfma_f32_16x16x32_bf16 v[42:45], v[154:157], v[194:197], v[42:45]
	v_mfma_f32_16x16x32_bf16 v[46:49], v[146:149], v[194:197], v[46:49]
	v_mfma_f32_16x16x32_bf16 v[30:33], v[146:149], v[202:205], v[30:33]
	v_mfma_f32_16x16x32_bf16 v[26:29], v[154:157], v[202:205], v[26:29]
	v_mfma_f32_16x16x32_bf16 v[8:11], v[154:157], v[210:213], v[8:11]
	v_mfma_f32_16x16x32_bf16 v[12:15], v[146:149], v[210:213], v[12:15]
	v_mfma_f32_16x16x32_bf16 v[54:57], v[158:161], v[182:185], v[54:57]
	v_mfma_f32_16x16x32_bf16 v[50:53], v[174:177], v[182:185], v[50:53]
	v_mfma_f32_16x16x32_bf16 v[34:37], v[174:177], v[190:193], v[34:37]
	v_mfma_f32_16x16x32_bf16 v[38:41], v[158:161], v[190:193], v[38:41]
	v_mfma_f32_16x16x32_bf16 v[22:25], v[158:161], v[198:201], v[22:25]
	v_mfma_f32_16x16x32_bf16 v[16:19], v[174:177], v[198:201], v[16:19]
	v_mfma_f32_16x16x32_bf16 v[0:3], v[174:177], v[206:209], v[0:3]
	v_mfma_f32_16x16x32_bf16 v[4:7], v[158:161], v[206:209], v[4:7]
	v_mfma_f32_16x16x32_bf16 v[54:57], v[170:173], v[186:189], v[54:57]
	v_mfma_f32_16x16x32_bf16 v[50:53], v[178:181], v[186:189], v[50:53]
	v_mfma_f32_16x16x32_bf16 v[34:37], v[178:181], v[194:197], v[34:37]
	v_mfma_f32_16x16x32_bf16 v[38:41], v[170:173], v[194:197], v[38:41]
	v_mfma_f32_16x16x32_bf16 v[22:25], v[170:173], v[202:205], v[22:25]
	v_mfma_f32_16x16x32_bf16 v[16:19], v[178:181], v[202:205], v[16:19]
	v_mfma_f32_16x16x32_bf16 v[0:3], v[178:181], v[210:213], v[0:3]
	v_mfma_f32_16x16x32_bf16 v[4:7], v[170:173], v[210:213], v[4:7]
	s_barrier
	s_setprio 0
	s_add_i32 s24, 0, 0x18000
	s_add_i32 s25, 0, 0x1c000
	v_add_u32_e32 v154, s24, v165
	v_add_u32_e32 v164, s25, v165
	ds_read_b128 v[142:145], v154
	ds_read_b128 v[146:149], v154 offset:1024
	ds_read_b128 v[150:153], v154 offset:2048
	ds_read_b128 v[154:157], v154 offset:3072
	ds_read_b128 v[158:161], v164
	ds_read_b128 v[170:173], v164 offset:1024
	ds_read_b128 v[174:177], v164 offset:2048
	ds_read_b128 v[178:181], v164 offset:3072
	s_add_u32 s74, s74, 0x80000
	s_addc_u32 s75, s75, 0
	s_mov_b32 m0, s27
	v_lshl_add_u64 v[222:223], s[74:75], 0, v[130:131]
	ds_read_b128 v[182:185], v169 offset:32768
	ds_read_b128 v[186:189], v169 offset:33792
	ds_read_b128 v[190:193], v169 offset:34816
	ds_read_b128 v[194:197], v169 offset:35840
	ds_read_b128 v[198:201], v169 offset:36864
	ds_read_b128 v[202:205], v169 offset:37888
	ds_read_b128 v[206:209], v169 offset:38912
	ds_read_b128 v[210:213], v169 offset:39936
	global_load_lds_dwordx4 v[222:223], off
	v_lshl_add_u64 v[222:223], s[74:75], 0, v[134:135]
	s_mov_b32 m0, s34
	s_nop 0
	global_load_lds_dwordx4 v[222:223], off
	s_waitcnt vmcnt(8)
	s_waitcnt lgkmcnt(0)
	s_setprio 1
	s_barrier
	v_mfma_f32_16x16x32_bf16 v[126:129], v[142:145], v[182:185], v[126:129]
	v_mfma_f32_16x16x32_bf16 v[122:125], v[150:153], v[182:185], v[122:125]
	v_mfma_f32_16x16x32_bf16 v[106:109], v[150:153], v[190:193], v[106:109]
	v_mfma_f32_16x16x32_bf16 v[110:113], v[142:145], v[190:193], v[110:113]
	v_mfma_f32_16x16x32_bf16 v[94:97], v[142:145], v[198:201], v[94:97]
	v_mfma_f32_16x16x32_bf16 v[90:93], v[150:153], v[198:201], v[90:93]
	v_mfma_f32_16x16x32_bf16 v[74:77], v[150:153], v[206:209], v[74:77]
	v_mfma_f32_16x16x32_bf16 v[78:81], v[142:145], v[206:209], v[78:81]
	v_mfma_f32_16x16x32_bf16 v[126:129], v[146:149], v[186:189], v[126:129]
	v_mfma_f32_16x16x32_bf16 v[122:125], v[154:157], v[186:189], v[122:125]
	v_mfma_f32_16x16x32_bf16 v[106:109], v[154:157], v[194:197], v[106:109]
	v_mfma_f32_16x16x32_bf16 v[110:113], v[146:149], v[194:197], v[110:113]
	v_mfma_f32_16x16x32_bf16 v[94:97], v[146:149], v[202:205], v[94:97]
	v_mfma_f32_16x16x32_bf16 v[90:93], v[154:157], v[202:205], v[90:93]
	v_mfma_f32_16x16x32_bf16 v[74:77], v[154:157], v[210:213], v[74:77]
	v_mfma_f32_16x16x32_bf16 v[78:81], v[146:149], v[210:213], v[78:81]
	v_mfma_f32_16x16x32_bf16 v[118:121], v[158:161], v[182:185], v[118:121]
	v_mfma_f32_16x16x32_bf16 v[114:117], v[174:177], v[182:185], v[114:117]
	v_mfma_f32_16x16x32_bf16 v[98:101], v[174:177], v[190:193], v[98:101]
	v_mfma_f32_16x16x32_bf16 v[102:105], v[158:161], v[190:193], v[102:105]
	v_mfma_f32_16x16x32_bf16 v[86:89], v[158:161], v[198:201], v[86:89]
	v_mfma_f32_16x16x32_bf16 v[82:85], v[174:177], v[198:201], v[82:85]
	v_mfma_f32_16x16x32_bf16 v[66:69], v[174:177], v[206:209], v[66:69]
	v_mfma_f32_16x16x32_bf16 v[70:73], v[158:161], v[206:209], v[70:73]
	v_mfma_f32_16x16x32_bf16 v[118:121], v[170:173], v[186:189], v[118:121]
	v_mfma_f32_16x16x32_bf16 v[114:117], v[178:181], v[186:189], v[114:117]
	v_mfma_f32_16x16x32_bf16 v[98:101], v[178:181], v[194:197], v[98:101]
	v_mfma_f32_16x16x32_bf16 v[102:105], v[170:173], v[194:197], v[102:105]
	v_mfma_f32_16x16x32_bf16 v[86:89], v[170:173], v[202:205], v[86:89]
	v_mfma_f32_16x16x32_bf16 v[82:85], v[178:181], v[202:205], v[82:85]
	v_mfma_f32_16x16x32_bf16 v[66:69], v[178:181], v[210:213], v[66:69]
	v_mfma_f32_16x16x32_bf16 v[70:73], v[170:173], v[210:213], v[70:73]
	s_barrier
; #define PG8_STAGE(bufoff, gbase, voff) do { _Pragma("unroll") for (int _i = 0; _i < 2; ++_i) \
;         __builtin_amdgcn_global_load_lds((const unsigned*)((const char*)(gbase) + (voff)[_i]), (PG8_LAS unsigned*)(lds + (bufoff) + ldsw + _i * 8192), 16, 0, 0); } while (0)
; #define PG8_LDA(dst, b, h) do { _Pragma("unroll") for (int m = 0; m < 4; ++m) _Pragma("unroll") for (int k = 0; k < 2; ++k) dst[m][k] = *(const PG8_LAS bf16x8*)(lds + PG8_SA(b, h) + aoff + m * 2048 + k * 1024); } while (0)
; #define PG8_MMA(ai, bj, At, Bt) do { __builtin_amdgcn_s_setprio(1); _Pragma("unroll") for (int m = 0; m < 4; ++m) _Pragma("unroll") for (int n = 0; n < 2; ++n) _Pragma("unroll") for (int k = 0; k < 2; ++k) \
;         acc[ai][bj][m][n] = __builtin_amdgcn_mfma_f32_16x16x32_bf16(Bt[n][k], At[m][k], acc[ai][bj][m][n], 0, 0, 0); __builtin_amdgcn_s_setprio(0); } while (0)
; #define PG8_WAIT_V(n) asm volatile("s_waitcnt vmcnt(" #n ")" ::: "memory")
; #define PG8_WAIT_L(n) asm volatile("s_waitcnt lgkmcnt(" #n ")" ::: "memory")
; #define PG8_BAR __builtin_amdgcn_s_barrier()
; #define PG8_SCHED __builtin_amdgcn_sched_barrier(0)
; template <class Epi, class Sched, bool ALIGN_EPI = false, bool SP2 = false>
; __device__ __forceinline__ void gemm_phase(PG8_LAS unsigned char* lds, const Gemm g, const Sched& S, const Epi& E, int tid_in) {
;     ...
;             PG8_LDA(At, 1, 1); PG8_STAGE(PG8_SB(1, 0), b3, voffB); PG8_STAGE(PG8_SB(1, 1), b3 + hstep, voffB); PG8_STAGE(PG8_SA(1, 0), a3, voffA);
;             PG8_WAIT_V(8); PG8_WAIT_L(0); PG8_BAR; PG8_MMA(1, 0, At, B0); PG8_MMA(1, 1, At, B1); PG8_BAR; PG8_SCHED;
	s_setprio 0
	s_add_i32 s24, s24, s15
	v_lshl_add_u64 v[162:163], v[162:163], 0, s[22:23]
	s_mov_b32 m0, s24
	ds_read_b128 v[182:185], v169 offset:49152
	ds_read_b128 v[186:189], v169 offset:50176
	ds_read_b128 v[190:193], v169 offset:51200
	ds_read_b128 v[194:197], v169 offset:52224
	ds_read_b128 v[198:201], v169 offset:53248
	ds_read_b128 v[202:205], v169 offset:54272
	ds_read_b128 v[206:209], v169 offset:55296
	ds_read_b128 v[210:213], v169 offset:56320
	global_load_lds_dwordx4 v[162:163], off
	s_add_i32 m0, s24, 0x2000
	s_add_u32 s72, s72, 0x80080
	v_lshl_add_u64 v[162:163], v[166:167], 0, s[22:23]
	s_addc_u32 s73, s73, 0
	s_add_i32 s24, s25, s15
	global_load_lds_dwordx4 v[162:163], off
	v_lshl_add_u64 v[162:163], s[72:73], 0, v[132:133]
	s_mov_b32 m0, s24
	s_nop 0
	global_load_lds_dwordx4 v[162:163], off
	v_lshl_add_u64 v[162:163], s[72:73], 0, v[136:137]
	s_add_i32 m0, s24, 0x2000
	s_nop 0
	global_load_lds_dwordx4 v[162:163], off
	v_lshl_add_u64 v[162:163], v[218:219], 0, s[22:23]
	s_mov_b32 m0, s69
	s_nop 0
	global_load_lds_dwordx4 v[162:163], off
	v_lshl_add_u64 v[162:163], v[220:221], 0, s[22:23]
	s_mov_b32 m0, s81
	s_nop 0
	global_load_lds_dwordx4 v[162:163], off
	s_waitcnt vmcnt(8)
	s_waitcnt lgkmcnt(0)
	s_setprio 1
	s_barrier
	v_mfma_f32_16x16x32_bf16 v[62:65], v[142:145], v[182:185], v[62:65]
	v_mfma_f32_16x16x32_bf16 v[58:61], v[150:153], v[182:185], v[58:61]
	v_mfma_f32_16x16x32_bf16 v[42:45], v[150:153], v[190:193], v[42:45]
	v_mfma_f32_16x16x32_bf16 v[46:49], v[142:145], v[190:193], v[46:49]
	v_mfma_f32_16x16x32_bf16 v[30:33], v[142:145], v[198:201], v[30:33]
	v_mfma_f32_16x16x32_bf16 v[26:29], v[150:153], v[198:201], v[26:29]
	v_mfma_f32_16x16x32_bf16 v[8:11], v[150:153], v[206:209], v[8:11]
	v_mfma_f32_16x16x32_bf16 v[12:15], v[142:145], v[206:209], v[12:15]
	v_mfma_f32_16x16x32_bf16 v[62:65], v[146:149], v[186:189], v[62:65]
	v_mfma_f32_16x16x32_bf16 v[58:61], v[154:157], v[186:189], v[58:61]
	v_mfma_f32_16x16x32_bf16 v[42:45], v[154:157], v[194:197], v[42:45]
	v_mfma_f32_16x16x32_bf16 v[46:49], v[146:149], v[194:197], v[46:49]
	v_mfma_f32_16x16x32_bf16 v[30:33], v[146:149], v[202:205], v[30:33]
	v_mfma_f32_16x16x32_bf16 v[26:29], v[154:157], v[202:205], v[26:29]
	v_mfma_f32_16x16x32_bf16 v[8:11], v[154:157], v[210:213], v[8:11]
	v_mfma_f32_16x16x32_bf16 v[12:15], v[146:149], v[210:213], v[12:15]
	v_mfma_f32_16x16x32_bf16 v[54:57], v[158:161], v[182:185], v[54:57]
	v_mfma_f32_16x16x32_bf16 v[50:53], v[174:177], v[182:185], v[50:53]
	v_mfma_f32_16x16x32_bf16 v[34:37], v[174:177], v[190:193], v[34:37]
	v_mfma_f32_16x16x32_bf16 v[38:41], v[158:161], v[190:193], v[38:41]
	v_mfma_f32_16x16x32_bf16 v[22:25], v[158:161], v[198:201], v[22:25]
	v_mfma_f32_16x16x32_bf16 v[16:19], v[174:177], v[198:201], v[16:19]
	v_mfma_f32_16x16x32_bf16 v[0:3], v[174:177], v[206:209], v[0:3]
	v_mfma_f32_16x16x32_bf16 v[4:7], v[158:161], v[206:209], v[4:7]
	v_mfma_f32_16x16x32_bf16 v[54:57], v[170:173], v[186:189], v[54:57]
	v_mfma_f32_16x16x32_bf16 v[50:53], v[178:181], v[186:189], v[50:53]
	v_mfma_f32_16x16x32_bf16 v[34:37], v[178:181], v[194:197], v[34:37]
	v_mfma_f32_16x16x32_bf16 v[38:41], v[170:173], v[194:197], v[38:41]
	v_mfma_f32_16x16x32_bf16 v[22:25], v[170:173], v[202:205], v[22:25]
	v_mfma_f32_16x16x32_bf16 v[16:19], v[178:181], v[202:205], v[16:19]
	v_mfma_f32_16x16x32_bf16 v[0:3], v[178:181], v[210:213], v[0:3]
	v_mfma_f32_16x16x32_bf16 v[4:7], v[170:173], v[210:213], v[4:7]
	s_barrier
	s_setprio 0
	s_add_i32 s95, s95, 2
	s_add_u32 s6, s6, 0x100
	s_addc_u32 s7, s7, 0
	s_add_u32 s87, s87, 0x100
	s_addc_u32 s90, s90, 0
	s_cmp_gt_u32 s95, 29
	s_cbranch_scc0 .LBB0_125
	s_and_b64 vcc, exec, s[58:59]
	s_cbranch_vccz .LBB0_128
	s_barrier

; #define PG8_STAGE(bufoff, gbase, voff) do { _Pragma("unroll") for (int _i = 0; _i < 2; ++_i) \
;         __builtin_amdgcn_global_load_lds((const unsigned*)((const char*)(gbase) + (voff)[_i]), (PG8_LAS unsigned*)(lds + (bufoff) + ldsw + _i * 8192), 16, 0, 0); } while (0)
; #define PG8_LDA(dst, b, h) do { _Pragma("unroll") for (int m = 0; m < 4; ++m) _Pragma("unroll") for (int k = 0; k < 2; ++k) dst[m][k] = *(const PG8_LAS bf16x8*)(lds + PG8_SA(b, h) + aoff + m * 2048 + k * 1024); } while (0)
; #define PG8_LDB(dst, b, h) do { _Pragma("unroll") for (int n = 0; n < 2; ++n) _Pragma("unroll") for (int k = 0; k < 2; ++k) dst[n][k] = *(const PG8_LAS bf16x8*)(lds + PG8_SB(b, h) + boff + n * 2048 + k * 1024); } while (0)
; #define PG8_MMA(ai, bj, At, Bt) do { __builtin_amdgcn_s_setprio(1); _Pragma("unroll") for (int m = 0; m < 4; ++m) _Pragma("unroll") for (int n = 0; n < 2; ++n) _Pragma("unroll") for (int k = 0; k < 2; ++k) \
;         acc[ai][bj][m][n] = __builtin_amdgcn_mfma_f32_16x16x32_bf16(Bt[n][k], At[m][k], acc[ai][bj][m][n], 0, 0, 0); __builtin_amdgcn_s_setprio(0); } while (0)
; #define PG8_WAIT_V(n) asm volatile("s_waitcnt vmcnt(" #n ")" ::: "memory")
; #define PG8_WAIT_L(n) asm volatile("s_waitcnt lgkmcnt(" #n ")" ::: "memory")
; template <class Epi, class Sched, bool ALIGN_EPI = false, bool SP2 = false>
; __device__ __forceinline__ void gemm_phase(PG8_LAS unsigned char* lds, const Gemm g, const Sched& S, const Epi& E, int tid_in) {
;     ...
;             const bool last = (t == nt - 2);
;             const char* a1 = cA + (size_t)(t + 1) * kstep;
;             const char* a2 = last ? nA : cA + (size_t)(t + 2) * kstep; const char* b2 = last ? nB : cB + (size_t)(t + 2) * kstep;
;             const char* a3 = a2 + kstep; const char* b3 = b2 + kstep;
;             if (last && has_next) S.a_ready(nxt);
;             if constexpr (SP2) {
;             PG8_LDB(B0, 0, 0); PG8_LDB(B1, 0, 1); PG8_SCHED; PG8_LDA(At, 0, 0); PG8_STAGE(PG8_SA(1, 1), a1 + hstep, voffA);
;             PG8_WAIT_V(8); PG8_WAIT_L(0); PG8_BAR; PG8_MMA(0, 0, At, B0); PG8_MMA(0, 1, At, B1); PG8_BAR; PG8_SCHED;
;             PG8_LDA(At, 0, 1); PG8_STAGE(PG8_SB(0, 0), b2, voffB); PG8_STAGE(PG8_SB(0, 1), b2 + hstep, voffB); PG8_STAGE(PG8_SA(0, 0), a2, voffA);
;             PG8_WAIT_V(8); PG8_WAIT_L(0); PG8_BAR; PG8_MMA(1, 0, At, B0); PG8_MMA(1, 1, At, B1); PG8_BAR; PG8_SCHED;
.LBB0_502:
	s_add_u32 s24, s8, 0xfff80080
	s_addc_u32 s25, s9, -1
	s_add_i32 s80, 0, 0x10000
	s_cmp_eq_u32 s79, 28
	s_cselect_b32 s71, s7, s25
	s_cselect_b32 s70, s18, s24
	s_cselect_b32 s69, s59, s78
	s_cselect_b32 s68, s61, s67
	s_add_i32 s24, 0, 0x14000
	v_add_u32_e32 v110, s80, v21
	v_add_u32_e32 v158, s24, v21
	ds_read_b128 v[74:77], v110
	ds_read_b128 v[94:97], v110 offset:1024
	ds_read_b128 v[102:105], v110 offset:2048
	ds_read_b128 v[110:113], v110 offset:3072
	ds_read_b128 v[122:125], v158
	ds_read_b128 v[138:141], v158 offset:1024
	ds_read_b128 v[146:149], v158 offset:2048
	ds_read_b128 v[158:161], v158 offset:3072
	v_lshl_add_u64 v[194:195], s[8:9], 0, v[226:227]
	s_add_i32 m0, s34, 0xc000
	ds_read_b128 v[162:165], v254
	ds_read_b128 v[166:169], v254 offset:1024
	ds_read_b128 v[170:173], v254 offset:2048
	ds_read_b128 v[174:177], v254 offset:3072
	ds_read_b128 v[178:181], v254 offset:4096
	ds_read_b128 v[182:185], v254 offset:5120
	ds_read_b128 v[186:189], v254 offset:6144
	ds_read_b128 v[190:193], v254 offset:7168
	global_load_lds_dwordx4 v[194:195], off
	v_lshl_add_u64 v[194:195], s[8:9], 0, v[228:229]
	s_add_i32 m0, s34, 0xe000
	s_nop 0
	global_load_lds_dwordx4 v[194:195], off
	s_waitcnt vmcnt(8)
	s_waitcnt lgkmcnt(0)
	s_setprio 1
	s_barrier
	v_mfma_f32_16x16x32_bf16 v[154:157], v[74:77], v[162:165], v[154:157]
	v_mfma_f32_16x16x32_bf16 v[150:153], v[102:105], v[162:165], v[150:153]
	v_mfma_f32_16x16x32_bf16 v[126:129], v[102:105], v[170:173], v[126:129]
	v_mfma_f32_16x16x32_bf16 v[130:133], v[74:77], v[170:173], v[130:133]
	v_mfma_f32_16x16x32_bf16 v[106:109], v[74:77], v[178:181], v[106:109]
	v_mfma_f32_16x16x32_bf16 v[98:101], v[102:105], v[178:181], v[98:101]
	v_mfma_f32_16x16x32_bf16 v[78:81], v[102:105], v[186:189], v[78:81]
	v_mfma_f32_16x16x32_bf16 v[82:85], v[74:77], v[186:189], v[82:85]
	v_mfma_f32_16x16x32_bf16 v[154:157], v[94:97], v[166:169], v[154:157]
	v_mfma_f32_16x16x32_bf16 v[150:153], v[110:113], v[166:169], v[150:153]
	v_mfma_f32_16x16x32_bf16 v[126:129], v[110:113], v[174:177], v[126:129]
	v_mfma_f32_16x16x32_bf16 v[130:133], v[94:97], v[174:177], v[130:133]
	v_mfma_f32_16x16x32_bf16 v[106:109], v[94:97], v[182:185], v[106:109]
	v_mfma_f32_16x16x32_bf16 v[98:101], v[110:113], v[182:185], v[98:101]
	v_mfma_f32_16x16x32_bf16 v[78:81], v[110:113], v[190:193], v[78:81]
	v_mfma_f32_16x16x32_bf16 v[82:85], v[94:97], v[190:193], v[82:85]
	v_mfma_f32_16x16x32_bf16 v[142:145], v[122:125], v[162:165], v[142:145]
	v_mfma_f32_16x16x32_bf16 v[134:137], v[146:149], v[162:165], v[134:137]
	v_mfma_f32_16x16x32_bf16 v[114:117], v[146:149], v[170:173], v[114:117]
	v_mfma_f32_16x16x32_bf16 v[118:121], v[122:125], v[170:173], v[118:121]
	v_mfma_f32_16x16x32_bf16 v[90:93], v[122:125], v[178:181], v[90:93]
	v_mfma_f32_16x16x32_bf16 v[86:89], v[146:149], v[178:181], v[86:89]
	v_mfma_f32_16x16x32_bf16 v[66:69], v[146:149], v[186:189], v[66:69]
	v_mfma_f32_16x16x32_bf16 v[70:73], v[122:125], v[186:189], v[70:73]
	v_mfma_f32_16x16x32_bf16 v[142:145], v[138:141], v[166:169], v[142:145]
	v_mfma_f32_16x16x32_bf16 v[134:137], v[158:161], v[166:169], v[134:137]
	v_mfma_f32_16x16x32_bf16 v[114:117], v[158:161], v[174:177], v[114:117]
	v_mfma_f32_16x16x32_bf16 v[118:121], v[138:141], v[174:177], v[118:121]
	v_mfma_f32_16x16x32_bf16 v[90:93], v[138:141], v[182:185], v[90:93]
	v_mfma_f32_16x16x32_bf16 v[86:89], v[158:161], v[182:185], v[86:89]
	v_mfma_f32_16x16x32_bf16 v[66:69], v[158:161], v[190:193], v[66:69]
	v_mfma_f32_16x16x32_bf16 v[70:73], v[138:141], v[190:193], v[70:73]
	s_barrier
	s_setprio 0
	s_add_i32 s25, s80, s14
	v_lshl_add_u64 v[194:195], s[68:69], 0, v[220:221]
	s_mov_b32 m0, s25
	ds_read_b128 v[162:165], v254 offset:16384
	ds_read_b128 v[166:169], v254 offset:17408
	ds_read_b128 v[170:173], v254 offset:18432
	ds_read_b128 v[174:177], v254 offset:19456
	ds_read_b128 v[178:181], v254 offset:20480
	ds_read_b128 v[182:185], v254 offset:21504
	ds_read_b128 v[186:189], v254 offset:22528
	ds_read_b128 v[190:193], v254 offset:23552
	global_load_lds_dwordx4 v[194:195], off
	s_add_i32 m0, s25, 0x2000
	s_add_u32 s80, s68, 0x80000
	v_lshl_add_u64 v[196:197], s[68:69], 0, v[224:225]
	s_addc_u32 s81, s69, 0
	s_add_i32 s24, s24, s14
	global_load_lds_dwordx4 v[196:197], off
	v_lshl_add_u64 v[198:199], s[80:81], 0, v[220:221]
	s_mov_b32 m0, s24
	v_lshl_add_u64 v[200:201], s[70:71], 0, v[222:223]
	global_load_lds_dwordx4 v[198:199], off
	v_lshl_add_u64 v[198:199], s[80:81], 0, v[224:225]
	s_add_i32 m0, s24, 0x2000
	s_nop 0
	global_load_lds_dwordx4 v[198:199], off
	v_lshl_add_u64 v[198:199], s[70:71], 0, v[218:219]
	s_mov_b32 m0, s34
	s_nop 0
	global_load_lds_dwordx4 v[198:199], off
	s_mov_b32 m0, s35
	s_nop 0
	global_load_lds_dwordx4 v[200:201], off
	s_waitcnt vmcnt(8)
	s_waitcnt lgkmcnt(0)
	s_setprio 1
	s_barrier
; #define PG8_STAGE(bufoff, gbase, voff) do { _Pragma("unroll") for (int _i = 0; _i < 2; ++_i) \
;         __builtin_amdgcn_global_load_lds((const unsigned*)((const char*)(gbase) + (voff)[_i]), (PG8_LAS unsigned*)(lds + (bufoff) + ldsw + _i * 8192), 16, 0, 0); } while (0)
; #define PG8_LDA(dst, b, h) do { _Pragma("unroll") for (int m = 0; m < 4; ++m) _Pragma("unroll") for (int k = 0; k < 2; ++k) dst[m][k] = *(const PG8_LAS bf16x8*)(lds + PG8_SA(b, h) + aoff + m * 2048 + k * 1024); } while (0)
; #define PG8_LDB(dst, b, h) do { _Pragma("unroll") for (int n = 0; n < 2; ++n) _Pragma("unroll") for (int k = 0; k < 2; ++k) dst[n][k] = *(const PG8_LAS bf16x8*)(lds + PG8_SB(b, h) + boff + n * 2048 + k * 1024); } while (0)
; #define PG8_MMA(ai, bj, At, Bt) do { __builtin_amdgcn_s_setprio(1); _Pragma("unroll") for (int m = 0; m < 4; ++m) _Pragma("unroll") for (int n = 0; n < 2; ++n) _Pragma("unroll") for (int k = 0; k < 2; ++k) \
;         acc[ai][bj][m][n] = __builtin_amdgcn_mfma_f32_16x16x32_bf16(Bt[n][k], At[m][k], acc[ai][bj][m][n], 0, 0, 0); __builtin_amdgcn_s_setprio(0); } while (0)
; #define PG8_WAIT_V(n) asm volatile("s_waitcnt vmcnt(" #n ")" ::: "memory")
; #define PG8_WAIT_L(n) asm volatile("s_waitcnt lgkmcnt(" #n ")" ::: "memory")
; #define PG8_BAR __builtin_amdgcn_s_barrier()
; #define PG8_SCHED __builtin_amdgcn_sched_barrier(0)
; template <class Epi, class Sched, bool ALIGN_EPI = false, bool SP2 = false>
; __device__ __forceinline__ void gemm_phase(PG8_LAS unsigned char* lds, const Gemm g, const Sched& S, const Epi& E, int tid_in) {
;     ...
;             PG8_WAIT_V(8); PG8_WAIT_L(0); PG8_BAR; PG8_MMA(1, 0, At, B0); PG8_MMA(1, 1, At, B1); PG8_BAR; PG8_SCHED;
;             PG8_LDB(B0, 1, 0); PG8_LDB(B1, 1, 1); PG8_SCHED; PG8_LDA(At, 1, 0); PG8_STAGE(PG8_SA(0, 1), a2 + hstep, voffA);
;             PG8_WAIT_V(8); PG8_WAIT_L(0); PG8_BAR; PG8_MMA(0, 0, At, B0); PG8_MMA(0, 1, At, B1); PG8_BAR; PG8_SCHED;
	v_mfma_f32_16x16x32_bf16 v[62:65], v[74:77], v[162:165], v[62:65]
	v_mfma_f32_16x16x32_bf16 v[58:61], v[102:105], v[162:165], v[58:61]
	v_mfma_f32_16x16x32_bf16 v[42:45], v[102:105], v[170:173], v[42:45]
	v_mfma_f32_16x16x32_bf16 v[46:49], v[74:77], v[170:173], v[46:49]
	v_mfma_f32_16x16x32_bf16 v[30:33], v[74:77], v[178:181], v[30:33]
	v_mfma_f32_16x16x32_bf16 v[26:29], v[102:105], v[178:181], v[26:29]
	v_mfma_f32_16x16x32_bf16 v[8:11], v[102:105], v[186:189], v[8:11]
	v_mfma_f32_16x16x32_bf16 v[12:15], v[74:77], v[186:189], v[12:15]
	v_mfma_f32_16x16x32_bf16 v[62:65], v[94:97], v[166:169], v[62:65]
	v_mfma_f32_16x16x32_bf16 v[58:61], v[110:113], v[166:169], v[58:61]
	v_mfma_f32_16x16x32_bf16 v[42:45], v[110:113], v[174:177], v[42:45]
	v_mfma_f32_16x16x32_bf16 v[46:49], v[94:97], v[174:177], v[46:49]
	v_mfma_f32_16x16x32_bf16 v[30:33], v[94:97], v[182:185], v[30:33]
	v_mfma_f32_16x16x32_bf16 v[26:29], v[110:113], v[182:185], v[26:29]
	v_mfma_f32_16x16x32_bf16 v[8:11], v[110:113], v[190:193], v[8:11]
	v_mfma_f32_16x16x32_bf16 v[12:15], v[94:97], v[190:193], v[12:15]
	v_mfma_f32_16x16x32_bf16 v[54:57], v[122:125], v[162:165], v[54:57]
	v_mfma_f32_16x16x32_bf16 v[50:53], v[146:149], v[162:165], v[50:53]
	v_mfma_f32_16x16x32_bf16 v[34:37], v[146:149], v[170:173], v[34:37]
	v_mfma_f32_16x16x32_bf16 v[38:41], v[122:125], v[170:173], v[38:41]
	v_mfma_f32_16x16x32_bf16 v[22:25], v[122:125], v[178:181], v[22:25]
	v_mfma_f32_16x16x32_bf16 v[16:19], v[146:149], v[178:181], v[16:19]
	v_mfma_f32_16x16x32_bf16 v[0:3], v[146:149], v[186:189], v[0:3]
	v_mfma_f32_16x16x32_bf16 v[4:7], v[122:125], v[186:189], v[4:7]
	v_mfma_f32_16x16x32_bf16 v[54:57], v[138:141], v[166:169], v[54:57]
	v_mfma_f32_16x16x32_bf16 v[50:53], v[158:161], v[166:169], v[50:53]
	v_mfma_f32_16x16x32_bf16 v[34:37], v[158:161], v[174:177], v[34:37]
	v_mfma_f32_16x16x32_bf16 v[38:41], v[138:141], v[174:177], v[38:41]
	v_mfma_f32_16x16x32_bf16 v[22:25], v[138:141], v[182:185], v[22:25]
	v_mfma_f32_16x16x32_bf16 v[16:19], v[158:161], v[182:185], v[16:19]
	v_mfma_f32_16x16x32_bf16 v[0:3], v[158:161], v[190:193], v[0:3]
	v_mfma_f32_16x16x32_bf16 v[4:7], v[138:141], v[190:193], v[4:7]
	s_barrier
	s_setprio 0
	s_add_i32 s24, 0, 0x18000
	s_add_i32 s25, 0, 0x1c000
	v_add_u32_e32 v110, s24, v21
	v_add_u32_e32 v158, s25, v21
	ds_read_b128 v[74:77], v110
	ds_read_b128 v[94:97], v110 offset:1024
	ds_read_b128 v[102:105], v110 offset:2048
	ds_read_b128 v[110:113], v110 offset:3072
	ds_read_b128 v[122:125], v158
	ds_read_b128 v[138:141], v158 offset:1024
	ds_read_b128 v[146:149], v158 offset:2048
	ds_read_b128 v[158:161], v158 offset:3072
	s_add_u32 s70, s70, 0x80000
	s_addc_u32 s71, s71, 0
	s_mov_b32 m0, s37
	v_lshl_add_u64 v[202:203], s[70:71], 0, v[218:219]
	ds_read_b128 v[162:165], v254 offset:32768
	ds_read_b128 v[166:169], v254 offset:33792
	ds_read_b128 v[170:173], v254 offset:34816
	ds_read_b128 v[174:177], v254 offset:35840
	ds_read_b128 v[178:181], v254 offset:36864
	ds_read_b128 v[182:185], v254 offset:37888
	ds_read_b128 v[186:189], v254 offset:38912
	ds_read_b128 v[190:193], v254 offset:39936
	global_load_lds_dwordx4 v[202:203], off
	v_lshl_add_u64 v[202:203], s[70:71], 0, v[222:223]
	s_mov_b32 m0, s38
	s_nop 0
	global_load_lds_dwordx4 v[202:203], off
	s_waitcnt vmcnt(8)
	s_waitcnt lgkmcnt(0)
	s_setprio 1
	s_barrier
	v_mfma_f32_16x16x32_bf16 v[154:157], v[74:77], v[162:165], v[154:157]
	v_mfma_f32_16x16x32_bf16 v[150:153], v[102:105], v[162:165], v[150:153]
	v_mfma_f32_16x16x32_bf16 v[126:129], v[102:105], v[170:173], v[126:129]
	v_mfma_f32_16x16x32_bf16 v[130:133], v[74:77], v[170:173], v[130:133]
	v_mfma_f32_16x16x32_bf16 v[106:109], v[74:77], v[178:181], v[106:109]
	v_mfma_f32_16x16x32_bf16 v[98:101], v[102:105], v[178:181], v[98:101]
	v_mfma_f32_16x16x32_bf16 v[78:81], v[102:105], v[186:189], v[78:81]
	v_mfma_f32_16x16x32_bf16 v[82:85], v[74:77], v[186:189], v[82:85]
	v_mfma_f32_16x16x32_bf16 v[154:157], v[94:97], v[166:169], v[154:157]
	v_mfma_f32_16x16x32_bf16 v[150:153], v[110:113], v[166:169], v[150:153]
	v_mfma_f32_16x16x32_bf16 v[126:129], v[110:113], v[174:177], v[126:129]
	v_mfma_f32_16x16x32_bf16 v[130:133], v[94:97], v[174:177], v[130:133]
	v_mfma_f32_16x16x32_bf16 v[106:109], v[94:97], v[182:185], v[106:109]
	v_mfma_f32_16x16x32_bf16 v[98:101], v[110:113], v[182:185], v[98:101]
	v_mfma_f32_16x16x32_bf16 v[78:81], v[110:113], v[190:193], v[78:81]
	v_mfma_f32_16x16x32_bf16 v[82:85], v[94:97], v[190:193], v[82:85]
	v_mfma_f32_16x16x32_bf16 v[142:145], v[122:125], v[162:165], v[142:145]
	v_mfma_f32_16x16x32_bf16 v[134:137], v[146:149], v[162:165], v[134:137]
	v_mfma_f32_16x16x32_bf16 v[114:117], v[146:149], v[170:173], v[114:117]
	v_mfma_f32_16x16x32_bf16 v[118:121], v[122:125], v[170:173], v[118:121]
	v_mfma_f32_16x16x32_bf16 v[90:93], v[122:125], v[178:181], v[90:93]
	v_mfma_f32_16x16x32_bf16 v[86:89], v[146:149], v[178:181], v[86:89]
	v_mfma_f32_16x16x32_bf16 v[66:69], v[146:149], v[186:189], v[66:69]
	v_mfma_f32_16x16x32_bf16 v[70:73], v[122:125], v[186:189], v[70:73]
	v_mfma_f32_16x16x32_bf16 v[142:145], v[138:141], v[166:169], v[142:145]
	v_mfma_f32_16x16x32_bf16 v[134:137], v[158:161], v[166:169], v[134:137]
	v_mfma_f32_16x16x32_bf16 v[114:117], v[158:161], v[174:177], v[114:117]
	v_mfma_f32_16x16x32_bf16 v[118:121], v[138:141], v[174:177], v[118:121]
	v_mfma_f32_16x16x32_bf16 v[90:93], v[138:141], v[182:185], v[90:93]
	v_mfma_f32_16x16x32_bf16 v[86:89], v[158:161], v[182:185], v[86:89]
	v_mfma_f32_16x16x32_bf16 v[66:69], v[158:161], v[190:193], v[66:69]
	v_mfma_f32_16x16x32_bf16 v[70:73], v[138:141], v[190:193], v[70:73]
	s_barrier
; #define PG8_STAGE(bufoff, gbase, voff) do { _Pragma("unroll") for (int _i = 0; _i < 2; ++_i) \
;         __builtin_amdgcn_global_load_lds((const unsigned*)((const char*)(gbase) + (voff)[_i]), (PG8_LAS unsigned*)(lds + (bufoff) + ldsw + _i * 8192), 16, 0, 0); } while (0)
; #define PG8_LDA(dst, b, h) do { _Pragma("unroll") for (int m = 0; m < 4; ++m) _Pragma("unroll") for (int k = 0; k < 2; ++k) dst[m][k] = *(const PG8_LAS bf16x8*)(lds + PG8_SA(b, h) + aoff + m * 2048 + k * 1024); } while (0)
; #define PG8_MMA(ai, bj, At, Bt) do { __builtin_amdgcn_s_setprio(1); _Pragma("unroll") for (int m = 0; m < 4; ++m) _Pragma("unroll") for (int n = 0; n < 2; ++n) _Pragma("unroll") for (int k = 0; k < 2; ++k) \
;         acc[ai][bj][m][n] = __builtin_amdgcn_mfma_f32_16x16x32_bf16(Bt[n][k], At[m][k], acc[ai][bj][m][n], 0, 0, 0); __builtin_amdgcn_s_setprio(0); } while (0)
; #define PG8_WAIT_V(n) asm volatile("s_waitcnt vmcnt(" #n ")" ::: "memory")
; #define PG8_WAIT_L(n) asm volatile("s_waitcnt lgkmcnt(" #n ")" ::: "memory")
; #define PG8_BAR __builtin_amdgcn_s_barrier()
; #define PG8_SCHED __builtin_amdgcn_sched_barrier(0)
; template <class Epi, class Sched, bool ALIGN_EPI = false, bool SP2 = false>
; __device__ __forceinline__ void gemm_phase(PG8_LAS unsigned char* lds, const Gemm g, const Sched& S, const Epi& E, int tid_in) {
;     ...
;             PG8_LDA(At, 1, 1); PG8_STAGE(PG8_SB(1, 0), b3, voffB); PG8_STAGE(PG8_SB(1, 1), b3 + hstep, voffB); PG8_STAGE(PG8_SA(1, 0), a3, voffA);
;             PG8_WAIT_V(8); PG8_WAIT_L(0); PG8_BAR; PG8_MMA(1, 0, At, B0); PG8_MMA(1, 1, At, B1); PG8_BAR; PG8_SCHED;
	s_setprio 0
	s_add_i32 s24, s24, s14
	v_lshl_add_u64 v[194:195], v[194:195], 0, s[22:23]
	s_mov_b32 m0, s24
	ds_read_b128 v[162:165], v254 offset:49152
	ds_read_b128 v[166:169], v254 offset:50176
	ds_read_b128 v[170:173], v254 offset:51200
	ds_read_b128 v[174:177], v254 offset:52224
	ds_read_b128 v[178:181], v254 offset:53248
	ds_read_b128 v[182:185], v254 offset:54272
	ds_read_b128 v[186:189], v254 offset:55296
	ds_read_b128 v[190:193], v254 offset:56320
	global_load_lds_dwordx4 v[194:195], off
	s_add_i32 m0, s24, 0x2000
	s_add_u32 s68, s68, 0x80080
	v_lshl_add_u64 v[194:195], v[196:197], 0, s[22:23]
	s_addc_u32 s69, s69, 0
	s_add_i32 s24, s25, s14
	global_load_lds_dwordx4 v[194:195], off
	v_lshl_add_u64 v[194:195], s[68:69], 0, v[220:221]
	s_mov_b32 m0, s24
	s_nop 0
	global_load_lds_dwordx4 v[194:195], off
	v_lshl_add_u64 v[194:195], s[68:69], 0, v[224:225]
	s_add_i32 m0, s24, 0x2000
	s_nop 0
	global_load_lds_dwordx4 v[194:195], off
	v_lshl_add_u64 v[194:195], v[198:199], 0, s[22:23]
	s_mov_b32 m0, s73
	s_nop 0
	global_load_lds_dwordx4 v[194:195], off
	v_lshl_add_u64 v[194:195], v[200:201], 0, s[22:23]
	s_mov_b32 m0, s74
	s_nop 0
	global_load_lds_dwordx4 v[194:195], off
	s_waitcnt vmcnt(8)
	s_waitcnt lgkmcnt(0)
	s_setprio 1
	s_barrier
	v_mfma_f32_16x16x32_bf16 v[62:65], v[74:77], v[162:165], v[62:65]
	v_mfma_f32_16x16x32_bf16 v[58:61], v[102:105], v[162:165], v[58:61]
	v_mfma_f32_16x16x32_bf16 v[42:45], v[102:105], v[170:173], v[42:45]
	v_mfma_f32_16x16x32_bf16 v[46:49], v[74:77], v[170:173], v[46:49]
	v_mfma_f32_16x16x32_bf16 v[30:33], v[74:77], v[178:181], v[30:33]
	v_mfma_f32_16x16x32_bf16 v[26:29], v[102:105], v[178:181], v[26:29]
	v_mfma_f32_16x16x32_bf16 v[8:11], v[102:105], v[186:189], v[8:11]
	v_mfma_f32_16x16x32_bf16 v[12:15], v[74:77], v[186:189], v[12:15]
	v_mfma_f32_16x16x32_bf16 v[62:65], v[94:97], v[166:169], v[62:65]
	v_mfma_f32_16x16x32_bf16 v[58:61], v[110:113], v[166:169], v[58:61]
	v_mfma_f32_16x16x32_bf16 v[42:45], v[110:113], v[174:177], v[42:45]
	v_mfma_f32_16x16x32_bf16 v[46:49], v[94:97], v[174:177], v[46:49]
	v_mfma_f32_16x16x32_bf16 v[30:33], v[94:97], v[182:185], v[30:33]
	v_mfma_f32_16x16x32_bf16 v[26:29], v[110:113], v[182:185], v[26:29]
	v_mfma_f32_16x16x32_bf16 v[8:11], v[110:113], v[190:193], v[8:11]
	v_mfma_f32_16x16x32_bf16 v[12:15], v[94:97], v[190:193], v[12:15]
	v_mfma_f32_16x16x32_bf16 v[54:57], v[122:125], v[162:165], v[54:57]
	v_mfma_f32_16x16x32_bf16 v[50:53], v[146:149], v[162:165], v[50:53]
	v_mfma_f32_16x16x32_bf16 v[34:37], v[146:149], v[170:173], v[34:37]
	v_mfma_f32_16x16x32_bf16 v[38:41], v[122:125], v[170:173], v[38:41]
	v_mfma_f32_16x16x32_bf16 v[22:25], v[122:125], v[178:181], v[22:25]
	v_mfma_f32_16x16x32_bf16 v[16:19], v[146:149], v[178:181], v[16:19]
	v_mfma_f32_16x16x32_bf16 v[0:3], v[146:149], v[186:189], v[0:3]
	v_mfma_f32_16x16x32_bf16 v[4:7], v[122:125], v[186:189], v[4:7]
	v_mfma_f32_16x16x32_bf16 v[54:57], v[138:141], v[166:169], v[54:57]
	v_mfma_f32_16x16x32_bf16 v[50:53], v[158:161], v[166:169], v[50:53]
	v_mfma_f32_16x16x32_bf16 v[34:37], v[158:161], v[174:177], v[34:37]
	v_mfma_f32_16x16x32_bf16 v[38:41], v[138:141], v[174:177], v[38:41]
	v_mfma_f32_16x16x32_bf16 v[22:25], v[138:141], v[182:185], v[22:25]
	v_mfma_f32_16x16x32_bf16 v[16:19], v[158:161], v[182:185], v[16:19]
	v_mfma_f32_16x16x32_bf16 v[0:3], v[158:161], v[190:193], v[0:3]
	v_mfma_f32_16x16x32_bf16 v[4:7], v[138:141], v[190:193], v[4:7]
	s_barrier
	s_setprio 0
	s_add_i32 s79, s79, 2
	s_add_u32 s8, s8, 0x100
	s_addc_u32 s9, s9, 0
	s_add_u32 s67, s67, 0x100
	s_addc_u32 s78, s78, 0
	s_cmp_gt_u32 s79, 29
	s_cbranch_scc0 .LBB0_502
	s_and_b64 vcc, exec, s[54:55]
	s_cbranch_vccz .LBB0_505
	s_barrier

; #define PG8_STAGE(bufoff, gbase, voff) do { _Pragma("unroll") for (int _i = 0; _i < 2; ++_i) \
;         __builtin_amdgcn_global_load_lds((const unsigned*)((const char*)(gbase) + (voff)[_i]), (PG8_LAS unsigned*)(lds + (bufoff) + ldsw + _i * 8192), 16, 0, 0); } while (0)
; #define PG8_LDA(dst, b, h) do { _Pragma("unroll") for (int m = 0; m < 4; ++m) _Pragma("unroll") for (int k = 0; k < 2; ++k) dst[m][k] = *(const PG8_LAS bf16x8*)(lds + PG8_SA(b, h) + aoff + m * 2048 + k * 1024); } while (0)
; #define PG8_LDB(dst, b, h) do { _Pragma("unroll") for (int n = 0; n < 2; ++n) _Pragma("unroll") for (int k = 0; k < 2; ++k) dst[n][k] = *(const PG8_LAS bf16x8*)(lds + PG8_SB(b, h) + boff + n * 2048 + k * 1024); } while (0)
; #define PG8_MMA(ai, bj, At, Bt) do { __builtin_amdgcn_s_setprio(1); _Pragma("unroll") for (int m = 0; m < 4; ++m) _Pragma("unroll") for (int n = 0; n < 2; ++n) _Pragma("unroll") for (int k = 0; k < 2; ++k) \
;         acc[ai][bj][m][n] = __builtin_amdgcn_mfma_f32_16x16x32_bf16(Bt[n][k], At[m][k], acc[ai][bj][m][n], 0, 0, 0); __builtin_amdgcn_s_setprio(0); } while (0)
; #define PG8_WAIT_V(n) asm volatile("s_waitcnt vmcnt(" #n ")" ::: "memory")
; #define PG8_WAIT_L(n) asm volatile("s_waitcnt lgkmcnt(" #n ")" ::: "memory")
; template <class Epi, class Sched, bool ALIGN_EPI = false, bool SP2 = false>
; __device__ __forceinline__ void gemm_phase(PG8_LAS unsigned char* lds, const Gemm g, const Sched& S, const Epi& E, int tid_in) {
;     ...
;             const bool last = (t == nt - 2);
;             const char* a1 = cA + (size_t)(t + 1) * kstep;
;             const char* a2 = last ? nA : cA + (size_t)(t + 2) * kstep; const char* b2 = last ? nB : cB + (size_t)(t + 2) * kstep;
;             const char* a3 = a2 + kstep; const char* b3 = b2 + kstep;
;             if (last && has_next) S.a_ready(nxt);
;             if constexpr (SP2) {
;             PG8_LDB(B0, 0, 0); PG8_LDB(B1, 0, 1); PG8_SCHED; PG8_LDA(At, 0, 0); PG8_STAGE(PG8_SA(1, 1), a1 + hstep, voffA);
;             PG8_WAIT_V(8); PG8_WAIT_L(0); PG8_BAR; PG8_MMA(0, 0, At, B0); PG8_MMA(0, 1, At, B1); PG8_BAR; PG8_SCHED;
;             PG8_LDA(At, 0, 1); PG8_STAGE(PG8_SB(0, 0), b2, voffB); PG8_STAGE(PG8_SB(0, 1), b2 + hstep, voffB); PG8_STAGE(PG8_SA(0, 0), a2, voffA);
;             PG8_WAIT_V(8); PG8_WAIT_L(0); PG8_BAR; PG8_MMA(1, 0, At, B0); PG8_MMA(1, 1, At, B1); PG8_BAR; PG8_SCHED;
.LBB0_716:
	s_add_u32 s10, s6, 0xfff80080
	s_addc_u32 s11, s7, -1
	s_add_i32 s24, 0, 0x10000
	s_cmp_eq_u32 vcc_lo, 28
	s_cselect_b32 s79, s9, s11
	s_cselect_b32 s78, s71, s10
	s_cselect_b32 s11, s69, s81
	s_cselect_b32 s10, s77, s80
	s_add_i32 vcc_hi, 0, 0x14000
	v_add_u32_e32 v142, s24, v21
	v_add_u32_e32 v158, vcc_hi, v21
	ds_read_b128 v[130:133], v142
	ds_read_b128 v[134:137], v142 offset:1024
	ds_read_b128 v[138:141], v142 offset:2048
	ds_read_b128 v[142:145], v142 offset:3072
	ds_read_b128 v[146:149], v158
	ds_read_b128 v[150:153], v158 offset:1024
	ds_read_b128 v[154:157], v158 offset:2048
	ds_read_b128 v[158:161], v158 offset:3072
	v_lshl_add_u64 v[206:207], s[6:7], 0, v[178:179]
	s_add_i32 m0, s27, 0xc000
	ds_read_b128 v[162:165], v254
	ds_read_b128 v[166:169], v254 offset:1024
	ds_read_b128 v[182:185], v254 offset:2048
	ds_read_b128 v[186:189], v254 offset:3072
	ds_read_b128 v[190:193], v254 offset:4096
	ds_read_b128 v[194:197], v254 offset:5120
	ds_read_b128 v[198:201], v254 offset:6144
	ds_read_b128 v[202:205], v254 offset:7168
	global_load_lds_dwordx4 v[206:207], off
	v_lshl_add_u64 v[206:207], s[6:7], 0, v[180:181]
	s_add_i32 m0, s27, 0xe000
	s_nop 0
	global_load_lds_dwordx4 v[206:207], off
	s_waitcnt vmcnt(8)
	s_waitcnt lgkmcnt(0)
	s_setprio 1
	s_barrier
	v_mfma_f32_16x16x32_bf16 v[126:129], v[130:133], v[162:165], v[126:129]
	v_mfma_f32_16x16x32_bf16 v[82:85], v[138:141], v[162:165], v[82:85]
	v_mfma_f32_16x16x32_bf16 v[46:49], v[138:141], v[182:185], v[46:49]
	v_mfma_f32_16x16x32_bf16 v[110:113], v[130:133], v[182:185], v[110:113]
	v_mfma_f32_16x16x32_bf16 v[106:109], v[130:133], v[190:193], v[106:109]
	v_mfma_f32_16x16x32_bf16 v[42:45], v[138:141], v[190:193], v[42:45]
	v_mfma_f32_16x16x32_bf16 v[50:53], v[138:141], v[198:201], v[50:53]
	v_mfma_f32_16x16x32_bf16 v[114:117], v[130:133], v[198:201], v[114:117]
	v_mfma_f32_16x16x32_bf16 v[126:129], v[134:137], v[166:169], v[126:129]
	v_mfma_f32_16x16x32_bf16 v[82:85], v[142:145], v[166:169], v[82:85]
	v_mfma_f32_16x16x32_bf16 v[46:49], v[142:145], v[186:189], v[46:49]
	v_mfma_f32_16x16x32_bf16 v[110:113], v[134:137], v[186:189], v[110:113]
	v_mfma_f32_16x16x32_bf16 v[106:109], v[134:137], v[194:197], v[106:109]
	v_mfma_f32_16x16x32_bf16 v[42:45], v[142:145], v[194:197], v[42:45]
	v_mfma_f32_16x16x32_bf16 v[50:53], v[142:145], v[202:205], v[50:53]
	v_mfma_f32_16x16x32_bf16 v[114:117], v[134:137], v[202:205], v[114:117]
	v_mfma_f32_16x16x32_bf16 v[122:125], v[146:149], v[162:165], v[122:125]
	v_mfma_f32_16x16x32_bf16 v[78:81], v[154:157], v[162:165], v[78:81]
	v_mfma_f32_16x16x32_bf16 v[38:41], v[154:157], v[182:185], v[38:41]
	v_mfma_f32_16x16x32_bf16 v[102:105], v[146:149], v[182:185], v[102:105]
	v_mfma_f32_16x16x32_bf16 v[98:101], v[146:149], v[190:193], v[98:101]
	v_mfma_f32_16x16x32_bf16 v[34:37], v[154:157], v[190:193], v[34:37]
	v_mfma_f32_16x16x32_bf16 v[54:57], v[154:157], v[198:201], v[54:57]
	v_mfma_f32_16x16x32_bf16 v[118:121], v[146:149], v[198:201], v[118:121]
	v_mfma_f32_16x16x32_bf16 v[122:125], v[150:153], v[166:169], v[122:125]
	v_mfma_f32_16x16x32_bf16 v[78:81], v[158:161], v[166:169], v[78:81]
	v_mfma_f32_16x16x32_bf16 v[38:41], v[158:161], v[186:189], v[38:41]
	v_mfma_f32_16x16x32_bf16 v[102:105], v[150:153], v[186:189], v[102:105]
	v_mfma_f32_16x16x32_bf16 v[98:101], v[150:153], v[194:197], v[98:101]
	v_mfma_f32_16x16x32_bf16 v[34:37], v[158:161], v[194:197], v[34:37]
	v_mfma_f32_16x16x32_bf16 v[54:57], v[158:161], v[202:205], v[54:57]
	v_mfma_f32_16x16x32_bf16 v[118:121], v[150:153], v[202:205], v[118:121]
	s_barrier
	s_setprio 0
	s_add_i32 s24, s24, s85
	v_lshl_add_u64 v[206:207], s[10:11], 0, v[172:173]
	s_mov_b32 m0, s24
	ds_read_b128 v[162:165], v254 offset:16384
	ds_read_b128 v[166:169], v254 offset:17408
	ds_read_b128 v[182:185], v254 offset:18432
	ds_read_b128 v[186:189], v254 offset:19456
	ds_read_b128 v[190:193], v254 offset:20480
	ds_read_b128 v[194:197], v254 offset:21504
	ds_read_b128 v[198:201], v254 offset:22528
	ds_read_b128 v[202:205], v254 offset:23552
	global_load_lds_dwordx4 v[206:207], off
	s_add_i32 m0, s24, 0x2000
	s_add_u32 s24, s10, 0x80000
	v_lshl_add_u64 v[208:209], s[10:11], 0, v[176:177]
	s_addc_u32 s25, s11, 0
	s_add_i32 vcc_hi, vcc_hi, s85
	global_load_lds_dwordx4 v[208:209], off
	v_lshl_add_u64 v[210:211], s[24:25], 0, v[172:173]
	s_mov_b32 m0, vcc_hi
	v_lshl_add_u64 v[212:213], s[78:79], 0, v[174:175]
	global_load_lds_dwordx4 v[210:211], off
	v_lshl_add_u64 v[210:211], s[24:25], 0, v[176:177]
	s_add_i32 m0, vcc_hi, 0x2000
	s_nop 0
	global_load_lds_dwordx4 v[210:211], off
	v_lshl_add_u64 v[210:211], s[78:79], 0, v[170:171]
	s_mov_b32 m0, s27
	s_nop 0
	global_load_lds_dwordx4 v[210:211], off
	s_mov_b32 m0, s87
	s_nop 0
	global_load_lds_dwordx4 v[212:213], off
	s_waitcnt vmcnt(8)
	s_waitcnt lgkmcnt(0)
	s_setprio 1
	s_barrier
; #define PG8_STAGE(bufoff, gbase, voff) do { _Pragma("unroll") for (int _i = 0; _i < 2; ++_i) \
;         __builtin_amdgcn_global_load_lds((const unsigned*)((const char*)(gbase) + (voff)[_i]), (PG8_LAS unsigned*)(lds + (bufoff) + ldsw + _i * 8192), 16, 0, 0); } while (0)
; #define PG8_LDA(dst, b, h) do { _Pragma("unroll") for (int m = 0; m < 4; ++m) _Pragma("unroll") for (int k = 0; k < 2; ++k) dst[m][k] = *(const PG8_LAS bf16x8*)(lds + PG8_SA(b, h) + aoff + m * 2048 + k * 1024); } while (0)
; #define PG8_LDB(dst, b, h) do { _Pragma("unroll") for (int n = 0; n < 2; ++n) _Pragma("unroll") for (int k = 0; k < 2; ++k) dst[n][k] = *(const PG8_LAS bf16x8*)(lds + PG8_SB(b, h) + boff + n * 2048 + k * 1024); } while (0)
; #define PG8_MMA(ai, bj, At, Bt) do { __builtin_amdgcn_s_setprio(1); _Pragma("unroll") for (int m = 0; m < 4; ++m) _Pragma("unroll") for (int n = 0; n < 2; ++n) _Pragma("unroll") for (int k = 0; k < 2; ++k) \
;         acc[ai][bj][m][n] = __builtin_amdgcn_mfma_f32_16x16x32_bf16(Bt[n][k], At[m][k], acc[ai][bj][m][n], 0, 0, 0); __builtin_amdgcn_s_setprio(0); } while (0)
; #define PG8_WAIT_V(n) asm volatile("s_waitcnt vmcnt(" #n ")" ::: "memory")
; #define PG8_WAIT_L(n) asm volatile("s_waitcnt lgkmcnt(" #n ")" ::: "memory")
; #define PG8_BAR __builtin_amdgcn_s_barrier()
; #define PG8_SCHED __builtin_amdgcn_sched_barrier(0)
; template <class Epi, class Sched, bool ALIGN_EPI = false, bool SP2 = false>
; __device__ __forceinline__ void gemm_phase(PG8_LAS unsigned char* lds, const Gemm g, const Sched& S, const Epi& E, int tid_in) {
;     ...
;             PG8_WAIT_V(8); PG8_WAIT_L(0); PG8_BAR; PG8_MMA(1, 0, At, B0); PG8_MMA(1, 1, At, B1); PG8_BAR; PG8_SCHED;
;             PG8_LDB(B0, 1, 0); PG8_LDB(B1, 1, 1); PG8_SCHED; PG8_LDA(At, 1, 0); PG8_STAGE(PG8_SA(0, 1), a2 + hstep, voffA);
;             PG8_WAIT_V(8); PG8_WAIT_L(0); PG8_BAR; PG8_MMA(0, 0, At, B0); PG8_MMA(0, 1, At, B1); PG8_BAR; PG8_SCHED;
	v_mfma_f32_16x16x32_bf16 v[86:89], v[130:133], v[162:165], v[86:89]
	v_mfma_f32_16x16x32_bf16 v[22:25], v[138:141], v[162:165], v[22:25]
	v_mfma_f32_16x16x32_bf16 v[12:15], v[138:141], v[182:185], v[12:15]
	v_mfma_f32_16x16x32_bf16 v[70:73], v[130:133], v[182:185], v[70:73]
	v_mfma_f32_16x16x32_bf16 v[66:69], v[130:133], v[190:193], v[66:69]
	v_mfma_f32_16x16x32_bf16 v[8:11], v[138:141], v[190:193], v[8:11]
	v_mfma_f32_16x16x32_bf16 v[26:29], v[138:141], v[198:201], v[26:29]
	v_mfma_f32_16x16x32_bf16 v[90:93], v[130:133], v[198:201], v[90:93]
	v_mfma_f32_16x16x32_bf16 v[86:89], v[134:137], v[166:169], v[86:89]
	v_mfma_f32_16x16x32_bf16 v[22:25], v[142:145], v[166:169], v[22:25]
	v_mfma_f32_16x16x32_bf16 v[12:15], v[142:145], v[186:189], v[12:15]
	v_mfma_f32_16x16x32_bf16 v[70:73], v[134:137], v[186:189], v[70:73]
	v_mfma_f32_16x16x32_bf16 v[66:69], v[134:137], v[194:197], v[66:69]
	v_mfma_f32_16x16x32_bf16 v[8:11], v[142:145], v[194:197], v[8:11]
	v_mfma_f32_16x16x32_bf16 v[26:29], v[142:145], v[202:205], v[26:29]
	v_mfma_f32_16x16x32_bf16 v[90:93], v[134:137], v[202:205], v[90:93]
	v_mfma_f32_16x16x32_bf16 v[74:77], v[146:149], v[162:165], v[74:77]
	v_mfma_f32_16x16x32_bf16 v[16:19], v[154:157], v[162:165], v[16:19]
	v_mfma_f32_16x16x32_bf16 v[4:7], v[154:157], v[182:185], v[4:7]
	v_mfma_f32_16x16x32_bf16 v[62:65], v[146:149], v[182:185], v[62:65]
	v_mfma_f32_16x16x32_bf16 v[58:61], v[146:149], v[190:193], v[58:61]
	v_mfma_f32_16x16x32_bf16 v[0:3], v[154:157], v[190:193], v[0:3]
	v_mfma_f32_16x16x32_bf16 v[30:33], v[154:157], v[198:201], v[30:33]
	v_mfma_f32_16x16x32_bf16 v[94:97], v[146:149], v[198:201], v[94:97]
	v_mfma_f32_16x16x32_bf16 v[74:77], v[150:153], v[166:169], v[74:77]
	v_mfma_f32_16x16x32_bf16 v[16:19], v[158:161], v[166:169], v[16:19]
	v_mfma_f32_16x16x32_bf16 v[4:7], v[158:161], v[186:189], v[4:7]
	v_mfma_f32_16x16x32_bf16 v[62:65], v[150:153], v[186:189], v[62:65]
	v_mfma_f32_16x16x32_bf16 v[58:61], v[150:153], v[194:197], v[58:61]
	v_mfma_f32_16x16x32_bf16 v[0:3], v[158:161], v[194:197], v[0:3]
	v_mfma_f32_16x16x32_bf16 v[30:33], v[158:161], v[202:205], v[30:33]
	v_mfma_f32_16x16x32_bf16 v[94:97], v[150:153], v[202:205], v[94:97]
	s_barrier
	s_setprio 0
	s_add_i32 vcc_hi, 0, 0x18000
	s_add_i32 s30, 0, 0x1c000
	v_add_u32_e32 v142, vcc_hi, v21
	v_add_u32_e32 v158, s30, v21
	ds_read_b128 v[130:133], v142
	ds_read_b128 v[134:137], v142 offset:1024
	ds_read_b128 v[138:141], v142 offset:2048
	ds_read_b128 v[142:145], v142 offset:3072
	ds_read_b128 v[146:149], v158
	ds_read_b128 v[150:153], v158 offset:1024
	ds_read_b128 v[154:157], v158 offset:2048
	ds_read_b128 v[158:161], v158 offset:3072
	s_add_u32 s24, s78, 0x80000
	s_addc_u32 s25, s79, 0
	s_mov_b32 m0, s38
	v_lshl_add_u64 v[218:219], s[24:25], 0, v[170:171]
	ds_read_b128 v[162:165], v254 offset:32768
	ds_read_b128 v[166:169], v254 offset:33792
	ds_read_b128 v[182:185], v254 offset:34816
	ds_read_b128 v[186:189], v254 offset:35840
	ds_read_b128 v[190:193], v254 offset:36864
	ds_read_b128 v[194:197], v254 offset:37888
	ds_read_b128 v[198:201], v254 offset:38912
	ds_read_b128 v[202:205], v254 offset:39936
	global_load_lds_dwordx4 v[218:219], off
	v_lshl_add_u64 v[218:219], s[24:25], 0, v[174:175]
	s_mov_b32 m0, s39
	s_nop 0
	global_load_lds_dwordx4 v[218:219], off
	s_waitcnt vmcnt(8)
	s_waitcnt lgkmcnt(0)
	s_setprio 1
	s_barrier
	v_mfma_f32_16x16x32_bf16 v[126:129], v[130:133], v[162:165], v[126:129]
	v_mfma_f32_16x16x32_bf16 v[82:85], v[138:141], v[162:165], v[82:85]
	v_mfma_f32_16x16x32_bf16 v[46:49], v[138:141], v[182:185], v[46:49]
	v_mfma_f32_16x16x32_bf16 v[110:113], v[130:133], v[182:185], v[110:113]
	v_mfma_f32_16x16x32_bf16 v[106:109], v[130:133], v[190:193], v[106:109]
	v_mfma_f32_16x16x32_bf16 v[42:45], v[138:141], v[190:193], v[42:45]
	v_mfma_f32_16x16x32_bf16 v[50:53], v[138:141], v[198:201], v[50:53]
	v_mfma_f32_16x16x32_bf16 v[114:117], v[130:133], v[198:201], v[114:117]
	v_mfma_f32_16x16x32_bf16 v[126:129], v[134:137], v[166:169], v[126:129]
	v_mfma_f32_16x16x32_bf16 v[82:85], v[142:145], v[166:169], v[82:85]
	v_mfma_f32_16x16x32_bf16 v[46:49], v[142:145], v[186:189], v[46:49]
	v_mfma_f32_16x16x32_bf16 v[110:113], v[134:137], v[186:189], v[110:113]
	v_mfma_f32_16x16x32_bf16 v[106:109], v[134:137], v[194:197], v[106:109]
	v_mfma_f32_16x16x32_bf16 v[42:45], v[142:145], v[194:197], v[42:45]
	v_mfma_f32_16x16x32_bf16 v[50:53], v[142:145], v[202:205], v[50:53]
	v_mfma_f32_16x16x32_bf16 v[114:117], v[134:137], v[202:205], v[114:117]
	v_mfma_f32_16x16x32_bf16 v[122:125], v[146:149], v[162:165], v[122:125]
	v_mfma_f32_16x16x32_bf16 v[78:81], v[154:157], v[162:165], v[78:81]
	v_mfma_f32_16x16x32_bf16 v[38:41], v[154:157], v[182:185], v[38:41]
	v_mfma_f32_16x16x32_bf16 v[102:105], v[146:149], v[182:185], v[102:105]
	v_mfma_f32_16x16x32_bf16 v[98:101], v[146:149], v[190:193], v[98:101]
	v_mfma_f32_16x16x32_bf16 v[34:37], v[154:157], v[190:193], v[34:37]
	v_mfma_f32_16x16x32_bf16 v[54:57], v[154:157], v[198:201], v[54:57]
	v_mfma_f32_16x16x32_bf16 v[118:121], v[146:149], v[198:201], v[118:121]
	v_mfma_f32_16x16x32_bf16 v[122:125], v[150:153], v[166:169], v[122:125]
	v_mfma_f32_16x16x32_bf16 v[78:81], v[158:161], v[166:169], v[78:81]
	v_mfma_f32_16x16x32_bf16 v[38:41], v[158:161], v[186:189], v[38:41]
	v_mfma_f32_16x16x32_bf16 v[102:105], v[150:153], v[186:189], v[102:105]
	v_mfma_f32_16x16x32_bf16 v[98:101], v[150:153], v[194:197], v[98:101]
	v_mfma_f32_16x16x32_bf16 v[34:37], v[158:161], v[194:197], v[34:37]
	v_mfma_f32_16x16x32_bf16 v[54:57], v[158:161], v[202:205], v[54:57]
	v_mfma_f32_16x16x32_bf16 v[118:121], v[150:153], v[202:205], v[118:121]
	s_barrier
; #define PG8_STAGE(bufoff, gbase, voff) do { _Pragma("unroll") for (int _i = 0; _i < 2; ++_i) \
;         __builtin_amdgcn_global_load_lds((const unsigned*)((const char*)(gbase) + (voff)[_i]), (PG8_LAS unsigned*)(lds + (bufoff) + ldsw + _i * 8192), 16, 0, 0); } while (0)
; #define PG8_LDA(dst, b, h) do { _Pragma("unroll") for (int m = 0; m < 4; ++m) _Pragma("unroll") for (int k = 0; k < 2; ++k) dst[m][k] = *(const PG8_LAS bf16x8*)(lds + PG8_SA(b, h) + aoff + m * 2048 + k * 1024); } while (0)
; #define PG8_MMA(ai, bj, At, Bt) do { __builtin_amdgcn_s_setprio(1); _Pragma("unroll") for (int m = 0; m < 4; ++m) _Pragma("unroll") for (int n = 0; n < 2; ++n) _Pragma("unroll") for (int k = 0; k < 2; ++k) \
;         acc[ai][bj][m][n] = __builtin_amdgcn_mfma_f32_16x16x32_bf16(Bt[n][k], At[m][k], acc[ai][bj][m][n], 0, 0, 0); __builtin_amdgcn_s_setprio(0); } while (0)
; #define PG8_WAIT_V(n) asm volatile("s_waitcnt vmcnt(" #n ")" ::: "memory")
; #define PG8_WAIT_L(n) asm volatile("s_waitcnt lgkmcnt(" #n ")" ::: "memory")
; #define PG8_BAR __builtin_amdgcn_s_barrier()
; #define PG8_SCHED __builtin_amdgcn_sched_barrier(0)
; template <class Epi, class Sched, bool ALIGN_EPI = false, bool SP2 = false>
; __device__ __forceinline__ void gemm_phase(PG8_LAS unsigned char* lds, const Gemm g, const Sched& S, const Epi& E, int tid_in) {
;     ...
;             PG8_LDA(At, 1, 1); PG8_STAGE(PG8_SB(1, 0), b3, voffB); PG8_STAGE(PG8_SB(1, 1), b3 + hstep, voffB); PG8_STAGE(PG8_SA(1, 0), a3, voffA);
;             PG8_WAIT_V(8); PG8_WAIT_L(0); PG8_BAR; PG8_MMA(1, 0, At, B0); PG8_MMA(1, 1, At, B1); PG8_BAR; PG8_SCHED;
	s_setprio 0
	s_add_i32 s24, vcc_hi, s85
	v_lshl_add_u64 v[206:207], v[206:207], 0, s[22:23]
	s_mov_b32 m0, s24
	ds_read_b128 v[162:165], v254 offset:49152
	ds_read_b128 v[166:169], v254 offset:50176
	ds_read_b128 v[182:185], v254 offset:51200
	ds_read_b128 v[186:189], v254 offset:52224
	ds_read_b128 v[190:193], v254 offset:53248
	ds_read_b128 v[194:197], v254 offset:54272
	ds_read_b128 v[198:201], v254 offset:55296
	ds_read_b128 v[202:205], v254 offset:56320
	global_load_lds_dwordx4 v[206:207], off
	s_add_i32 m0, s24, 0x2000
	s_add_u32 s10, s10, 0x80080
	v_lshl_add_u64 v[206:207], v[208:209], 0, s[22:23]
	s_addc_u32 s11, s11, 0
	s_add_i32 s24, s30, s85
	global_load_lds_dwordx4 v[206:207], off
	v_lshl_add_u64 v[206:207], s[10:11], 0, v[172:173]
	s_mov_b32 m0, s24
	s_nop 0
	global_load_lds_dwordx4 v[206:207], off
	v_lshl_add_u64 v[206:207], s[10:11], 0, v[176:177]
	s_add_i32 m0, s24, 0x2000
	s_nop 0
	global_load_lds_dwordx4 v[206:207], off
	v_lshl_add_u64 v[206:207], v[210:211], 0, s[22:23]
	s_mov_b32 m0, s26
	s_nop 0
	global_load_lds_dwordx4 v[206:207], off
	v_lshl_add_u64 v[206:207], v[212:213], 0, s[22:23]
	s_mov_b32 m0, s90
	s_nop 0
	global_load_lds_dwordx4 v[206:207], off
	s_waitcnt vmcnt(8)
	s_waitcnt lgkmcnt(0)
	s_setprio 1
	s_barrier
	v_mfma_f32_16x16x32_bf16 v[86:89], v[130:133], v[162:165], v[86:89]
	v_mfma_f32_16x16x32_bf16 v[22:25], v[138:141], v[162:165], v[22:25]
	v_mfma_f32_16x16x32_bf16 v[12:15], v[138:141], v[182:185], v[12:15]
	v_mfma_f32_16x16x32_bf16 v[70:73], v[130:133], v[182:185], v[70:73]
	v_mfma_f32_16x16x32_bf16 v[66:69], v[130:133], v[190:193], v[66:69]
	v_mfma_f32_16x16x32_bf16 v[8:11], v[138:141], v[190:193], v[8:11]
	v_mfma_f32_16x16x32_bf16 v[26:29], v[138:141], v[198:201], v[26:29]
	v_mfma_f32_16x16x32_bf16 v[90:93], v[130:133], v[198:201], v[90:93]
	v_mfma_f32_16x16x32_bf16 v[86:89], v[134:137], v[166:169], v[86:89]
	v_mfma_f32_16x16x32_bf16 v[22:25], v[142:145], v[166:169], v[22:25]
	v_mfma_f32_16x16x32_bf16 v[12:15], v[142:145], v[186:189], v[12:15]
	v_mfma_f32_16x16x32_bf16 v[70:73], v[134:137], v[186:189], v[70:73]
	v_mfma_f32_16x16x32_bf16 v[66:69], v[134:137], v[194:197], v[66:69]
	v_mfma_f32_16x16x32_bf16 v[8:11], v[142:145], v[194:197], v[8:11]
	v_mfma_f32_16x16x32_bf16 v[26:29], v[142:145], v[202:205], v[26:29]
	v_mfma_f32_16x16x32_bf16 v[90:93], v[134:137], v[202:205], v[90:93]
	v_mfma_f32_16x16x32_bf16 v[74:77], v[146:149], v[162:165], v[74:77]
	v_mfma_f32_16x16x32_bf16 v[16:19], v[154:157], v[162:165], v[16:19]
	v_mfma_f32_16x16x32_bf16 v[4:7], v[154:157], v[182:185], v[4:7]
	v_mfma_f32_16x16x32_bf16 v[62:65], v[146:149], v[182:185], v[62:65]
	v_mfma_f32_16x16x32_bf16 v[58:61], v[146:149], v[190:193], v[58:61]
	v_mfma_f32_16x16x32_bf16 v[0:3], v[154:157], v[190:193], v[0:3]
	v_mfma_f32_16x16x32_bf16 v[30:33], v[154:157], v[198:201], v[30:33]
	v_mfma_f32_16x16x32_bf16 v[94:97], v[146:149], v[198:201], v[94:97]
	v_mfma_f32_16x16x32_bf16 v[74:77], v[150:153], v[166:169], v[74:77]
	v_mfma_f32_16x16x32_bf16 v[16:19], v[158:161], v[166:169], v[16:19]
	v_mfma_f32_16x16x32_bf16 v[4:7], v[158:161], v[186:189], v[4:7]
	v_mfma_f32_16x16x32_bf16 v[62:65], v[150:153], v[186:189], v[62:65]
	v_mfma_f32_16x16x32_bf16 v[58:61], v[150:153], v[194:197], v[58:61]
	v_mfma_f32_16x16x32_bf16 v[0:3], v[158:161], v[194:197], v[0:3]
	v_mfma_f32_16x16x32_bf16 v[30:33], v[158:161], v[202:205], v[30:33]
	v_mfma_f32_16x16x32_bf16 v[94:97], v[150:153], v[202:205], v[94:97]
	s_barrier
	s_setprio 0
	s_add_i32 vcc_lo, vcc_lo, 2
	s_add_u32 s6, s6, 0x100
	s_addc_u32 s7, s7, 0
	s_add_u32 s80, s80, 0x100
	s_addc_u32 s81, s81, 0
	s_cmp_gt_u32 vcc_lo, 29
	s_cbranch_scc0 .LBB0_716
	s_and_b64 vcc, exec, s[60:61]
	s_cbranch_vccz .LBB0_719
	s_barrier

; #define PG8_STAGE(bufoff, gbase, voff) do { _Pragma("unroll") for (int _i = 0; _i < 2; ++_i) \
;         __builtin_amdgcn_global_load_lds((const unsigned*)((const char*)(gbase) + (voff)[_i]), (PG8_LAS unsigned*)(lds + (bufoff) + ldsw + _i * 8192), 16, 0, 0); } while (0)
; #define PG8_LDA(dst, b, h) do { _Pragma("unroll") for (int m = 0; m < 4; ++m) _Pragma("unroll") for (int k = 0; k < 2; ++k) dst[m][k] = *(const PG8_LAS bf16x8*)(lds + PG8_SA(b, h) + aoff + m * 2048 + k * 1024); } while (0)
; #define PG8_LDB(dst, b, h) do { _Pragma("unroll") for (int n = 0; n < 2; ++n) _Pragma("unroll") for (int k = 0; k < 2; ++k) dst[n][k] = *(const PG8_LAS bf16x8*)(lds + PG8_SB(b, h) + boff + n * 2048 + k * 1024); } while (0)
; #define PG8_MMA(ai, bj, At, Bt) do { __builtin_amdgcn_s_setprio(1); _Pragma("unroll") for (int m = 0; m < 4; ++m) _Pragma("unroll") for (int n = 0; n < 2; ++n) _Pragma("unroll") for (int k = 0; k < 2; ++k) \
;         acc[ai][bj][m][n] = __builtin_amdgcn_mfma_f32_16x16x32_bf16(Bt[n][k], At[m][k], acc[ai][bj][m][n], 0, 0, 0); __builtin_amdgcn_s_setprio(0); } while (0)
; #define PG8_WAIT_V(n) asm volatile("s_waitcnt vmcnt(" #n ")" ::: "memory")
; #define PG8_WAIT_L(n) asm volatile("s_waitcnt lgkmcnt(" #n ")" ::: "memory")
; template <class Epi, class Sched, bool ALIGN_EPI = false, bool SP2 = false>
; __device__ __forceinline__ void gemm_phase(PG8_LAS unsigned char* lds, const Gemm g, const Sched& S, const Epi& E, int tid_in) {
;     ...
;             const bool last = (t == nt - 2);
;             const char* a1 = cA + (size_t)(t + 1) * kstep;
;             const char* a2 = last ? nA : cA + (size_t)(t + 2) * kstep; const char* b2 = last ? nB : cB + (size_t)(t + 2) * kstep;
;             const char* a3 = a2 + kstep; const char* b3 = b2 + kstep;
;             if (last && has_next) S.a_ready(nxt);
;             if constexpr (SP2) {
;             PG8_LDB(B0, 0, 0); PG8_LDB(B1, 0, 1); PG8_SCHED; PG8_LDA(At, 0, 0); PG8_STAGE(PG8_SA(1, 1), a1 + hstep, voffA);
;             PG8_WAIT_V(8); PG8_WAIT_L(0); PG8_BAR; PG8_MMA(0, 0, At, B0); PG8_MMA(0, 1, At, B1); PG8_BAR; PG8_SCHED;
;             PG8_LDA(At, 0, 1); PG8_STAGE(PG8_SB(0, 0), b2, voffB); PG8_STAGE(PG8_SB(0, 1), b2 + hstep, voffB); PG8_STAGE(PG8_SA(0, 0), a2, voffA);
;             PG8_WAIT_V(8); PG8_WAIT_L(0); PG8_BAR; PG8_MMA(1, 0, At, B0); PG8_MMA(1, 1, At, B1); PG8_BAR; PG8_SCHED;
.LBB0_891:
	s_add_u32 s6, s8, 0x100
	s_addc_u32 s7, s9, 0
	s_add_i32 s24, 0, 0x10000
	s_cmpk_eq_i32 s79, 0x54
	s_cselect_b32 s67, s63, s7
	s_cselect_b32 s66, s62, s6
	s_cselect_b32 s11, s65, s78
	s_cselect_b32 s10, s64, s69
	s_add_i32 s25, 0, 0x14000
	v_add_u32_e32 v102, s24, v21
	v_add_u32_e32 v150, s25, v21
	ds_read_b128 v[66:69], v102
	ds_read_b128 v[78:81], v102 offset:1024
	ds_read_b128 v[90:93], v102 offset:2048
	ds_read_b128 v[102:105], v102 offset:3072
	ds_read_b128 v[114:117], v150
	ds_read_b128 v[126:129], v150 offset:1024
	ds_read_b128 v[138:141], v150 offset:2048
	ds_read_b128 v[150:153], v150 offset:3072
	v_lshl_add_u64 v[206:207], s[8:9], 0, v[198:199]
	s_add_i32 m0, s34, 0xc000
	ds_read_b128 v[162:165], v228
	ds_read_b128 v[166:169], v228 offset:1024
	ds_read_b128 v[170:173], v228 offset:2048
	ds_read_b128 v[174:177], v228 offset:3072
	ds_read_b128 v[178:181], v228 offset:4096
	ds_read_b128 v[182:185], v228 offset:5120
	ds_read_b128 v[186:189], v228 offset:6144
	ds_read_b128 v[202:205], v228 offset:7168
	global_load_lds_dwordx4 v[206:207], off
	v_lshl_add_u64 v[206:207], s[8:9], 0, v[200:201]
	s_add_i32 m0, s34, 0xe000
	s_nop 0
	global_load_lds_dwordx4 v[206:207], off
	s_waitcnt vmcnt(8)
	s_waitcnt lgkmcnt(0)
	s_setprio 1
	s_barrier
	v_mfma_f32_16x16x32_bf16 v[158:161], v[66:69], v[162:165], v[158:161]
	v_mfma_f32_16x16x32_bf16 v[154:157], v[90:93], v[162:165], v[154:157]
	v_mfma_f32_16x16x32_bf16 v[130:133], v[90:93], v[170:173], v[130:133]
	v_mfma_f32_16x16x32_bf16 v[134:137], v[66:69], v[170:173], v[134:137]
	v_mfma_f32_16x16x32_bf16 v[110:113], v[66:69], v[178:181], v[110:113]
	v_mfma_f32_16x16x32_bf16 v[106:109], v[90:93], v[178:181], v[106:109]
	v_mfma_f32_16x16x32_bf16 v[82:85], v[90:93], v[186:189], v[82:85]
	v_mfma_f32_16x16x32_bf16 v[86:89], v[66:69], v[186:189], v[86:89]
	v_mfma_f32_16x16x32_bf16 v[158:161], v[78:81], v[166:169], v[158:161]
	v_mfma_f32_16x16x32_bf16 v[154:157], v[102:105], v[166:169], v[154:157]
	v_mfma_f32_16x16x32_bf16 v[130:133], v[102:105], v[174:177], v[130:133]
	v_mfma_f32_16x16x32_bf16 v[134:137], v[78:81], v[174:177], v[134:137]
	v_mfma_f32_16x16x32_bf16 v[110:113], v[78:81], v[182:185], v[110:113]
	v_mfma_f32_16x16x32_bf16 v[106:109], v[102:105], v[182:185], v[106:109]
	v_mfma_f32_16x16x32_bf16 v[82:85], v[102:105], v[202:205], v[82:85]
	v_mfma_f32_16x16x32_bf16 v[86:89], v[78:81], v[202:205], v[86:89]
	v_mfma_f32_16x16x32_bf16 v[146:149], v[114:117], v[162:165], v[146:149]
	v_mfma_f32_16x16x32_bf16 v[142:145], v[138:141], v[162:165], v[142:145]
	v_mfma_f32_16x16x32_bf16 v[118:121], v[138:141], v[170:173], v[118:121]
	v_mfma_f32_16x16x32_bf16 v[122:125], v[114:117], v[170:173], v[122:125]
	v_mfma_f32_16x16x32_bf16 v[98:101], v[114:117], v[178:181], v[98:101]
	v_mfma_f32_16x16x32_bf16 v[94:97], v[138:141], v[178:181], v[94:97]
	v_mfma_f32_16x16x32_bf16 v[70:73], v[138:141], v[186:189], v[70:73]
	v_mfma_f32_16x16x32_bf16 v[74:77], v[114:117], v[186:189], v[74:77]
	v_mfma_f32_16x16x32_bf16 v[146:149], v[126:129], v[166:169], v[146:149]
	v_mfma_f32_16x16x32_bf16 v[142:145], v[150:153], v[166:169], v[142:145]
	v_mfma_f32_16x16x32_bf16 v[118:121], v[150:153], v[174:177], v[118:121]
	v_mfma_f32_16x16x32_bf16 v[122:125], v[126:129], v[174:177], v[122:125]
	v_mfma_f32_16x16x32_bf16 v[98:101], v[126:129], v[182:185], v[98:101]
	v_mfma_f32_16x16x32_bf16 v[94:97], v[150:153], v[182:185], v[94:97]
	v_mfma_f32_16x16x32_bf16 v[70:73], v[150:153], v[202:205], v[70:73]
	v_mfma_f32_16x16x32_bf16 v[74:77], v[126:129], v[202:205], v[74:77]
	s_barrier
	s_setprio 0
	s_add_i32 s8, s24, s14
	v_lshl_add_u64 v[206:207], s[10:11], 0, v[192:193]
	s_mov_b32 m0, s8
	ds_read_b128 v[162:165], v228 offset:16384
	ds_read_b128 v[166:169], v228 offset:17408
	ds_read_b128 v[170:173], v228 offset:18432
	ds_read_b128 v[174:177], v228 offset:19456
	ds_read_b128 v[178:181], v228 offset:20480
	ds_read_b128 v[182:185], v228 offset:21504
	ds_read_b128 v[186:189], v228 offset:22528
	ds_read_b128 v[202:205], v228 offset:23552
	global_load_lds_dwordx4 v[206:207], off
	s_add_i32 m0, s8, 0x2000
	s_add_u32 s8, s10, 0x160000
	v_lshl_add_u64 v[208:209], s[10:11], 0, v[196:197]
	s_addc_u32 s9, s11, 0
	s_add_i32 s24, s25, s14
	global_load_lds_dwordx4 v[208:209], off
	v_lshl_add_u64 v[210:211], s[8:9], 0, v[192:193]
	s_mov_b32 m0, s24
	v_lshl_add_u64 v[212:213], s[66:67], 0, v[194:195]
	global_load_lds_dwordx4 v[210:211], off
	v_lshl_add_u64 v[210:211], s[8:9], 0, v[196:197]
	s_add_i32 m0, s24, 0x2000
	s_nop 0
	global_load_lds_dwordx4 v[210:211], off
	v_lshl_add_u64 v[210:211], s[66:67], 0, v[190:191]
	s_mov_b32 m0, s34
	s_nop 0
	global_load_lds_dwordx4 v[210:211], off
	s_mov_b32 m0, s35
	s_nop 0
	global_load_lds_dwordx4 v[212:213], off
	s_waitcnt vmcnt(8)
	s_waitcnt lgkmcnt(0)
	s_setprio 1
	s_barrier
; #define PG8_STAGE(bufoff, gbase, voff) do { _Pragma("unroll") for (int _i = 0; _i < 2; ++_i) \
;         __builtin_amdgcn_global_load_lds((const unsigned*)((const char*)(gbase) + (voff)[_i]), (PG8_LAS unsigned*)(lds + (bufoff) + ldsw + _i * 8192), 16, 0, 0); } while (0)
; #define PG8_LDA(dst, b, h) do { _Pragma("unroll") for (int m = 0; m < 4; ++m) _Pragma("unroll") for (int k = 0; k < 2; ++k) dst[m][k] = *(const PG8_LAS bf16x8*)(lds + PG8_SA(b, h) + aoff + m * 2048 + k * 1024); } while (0)
; #define PG8_LDB(dst, b, h) do { _Pragma("unroll") for (int n = 0; n < 2; ++n) _Pragma("unroll") for (int k = 0; k < 2; ++k) dst[n][k] = *(const PG8_LAS bf16x8*)(lds + PG8_SB(b, h) + boff + n * 2048 + k * 1024); } while (0)
; #define PG8_MMA(ai, bj, At, Bt) do { __builtin_amdgcn_s_setprio(1); _Pragma("unroll") for (int m = 0; m < 4; ++m) _Pragma("unroll") for (int n = 0; n < 2; ++n) _Pragma("unroll") for (int k = 0; k < 2; ++k) \
;         acc[ai][bj][m][n] = __builtin_amdgcn_mfma_f32_16x16x32_bf16(Bt[n][k], At[m][k], acc[ai][bj][m][n], 0, 0, 0); __builtin_amdgcn_s_setprio(0); } while (0)
; #define PG8_WAIT_V(n) asm volatile("s_waitcnt vmcnt(" #n ")" ::: "memory")
; #define PG8_WAIT_L(n) asm volatile("s_waitcnt lgkmcnt(" #n ")" ::: "memory")
; #define PG8_BAR __builtin_amdgcn_s_barrier()
; #define PG8_SCHED __builtin_amdgcn_sched_barrier(0)
; template <class Epi, class Sched, bool ALIGN_EPI = false, bool SP2 = false>
; __device__ __forceinline__ void gemm_phase(PG8_LAS unsigned char* lds, const Gemm g, const Sched& S, const Epi& E, int tid_in) {
;     ...
;             PG8_WAIT_V(8); PG8_WAIT_L(0); PG8_BAR; PG8_MMA(1, 0, At, B0); PG8_MMA(1, 1, At, B1); PG8_BAR; PG8_SCHED;
;             PG8_LDB(B0, 1, 0); PG8_LDB(B1, 1, 1); PG8_SCHED; PG8_LDA(At, 1, 0); PG8_STAGE(PG8_SA(0, 1), a2 + hstep, voffA);
;             PG8_WAIT_V(8); PG8_WAIT_L(0); PG8_BAR; PG8_MMA(0, 0, At, B0); PG8_MMA(0, 1, At, B1); PG8_BAR; PG8_SCHED;
	v_mfma_f32_16x16x32_bf16 v[62:65], v[66:69], v[162:165], v[62:65]
	v_mfma_f32_16x16x32_bf16 v[58:61], v[90:93], v[162:165], v[58:61]
	v_mfma_f32_16x16x32_bf16 v[42:45], v[90:93], v[170:173], v[42:45]
	v_mfma_f32_16x16x32_bf16 v[46:49], v[66:69], v[170:173], v[46:49]
	v_mfma_f32_16x16x32_bf16 v[30:33], v[66:69], v[178:181], v[30:33]
	v_mfma_f32_16x16x32_bf16 v[26:29], v[90:93], v[178:181], v[26:29]
	v_mfma_f32_16x16x32_bf16 v[8:11], v[90:93], v[186:189], v[8:11]
	v_mfma_f32_16x16x32_bf16 v[12:15], v[66:69], v[186:189], v[12:15]
	v_mfma_f32_16x16x32_bf16 v[62:65], v[78:81], v[166:169], v[62:65]
	v_mfma_f32_16x16x32_bf16 v[58:61], v[102:105], v[166:169], v[58:61]
	v_mfma_f32_16x16x32_bf16 v[42:45], v[102:105], v[174:177], v[42:45]
	v_mfma_f32_16x16x32_bf16 v[46:49], v[78:81], v[174:177], v[46:49]
	v_mfma_f32_16x16x32_bf16 v[30:33], v[78:81], v[182:185], v[30:33]
	v_mfma_f32_16x16x32_bf16 v[26:29], v[102:105], v[182:185], v[26:29]
	v_mfma_f32_16x16x32_bf16 v[8:11], v[102:105], v[202:205], v[8:11]
	v_mfma_f32_16x16x32_bf16 v[12:15], v[78:81], v[202:205], v[12:15]
	v_mfma_f32_16x16x32_bf16 v[54:57], v[114:117], v[162:165], v[54:57]
	v_mfma_f32_16x16x32_bf16 v[50:53], v[138:141], v[162:165], v[50:53]
	v_mfma_f32_16x16x32_bf16 v[34:37], v[138:141], v[170:173], v[34:37]
	v_mfma_f32_16x16x32_bf16 v[38:41], v[114:117], v[170:173], v[38:41]
	v_mfma_f32_16x16x32_bf16 v[22:25], v[114:117], v[178:181], v[22:25]
	v_mfma_f32_16x16x32_bf16 v[16:19], v[138:141], v[178:181], v[16:19]
	v_mfma_f32_16x16x32_bf16 v[0:3], v[138:141], v[186:189], v[0:3]
	v_mfma_f32_16x16x32_bf16 v[4:7], v[114:117], v[186:189], v[4:7]
	v_mfma_f32_16x16x32_bf16 v[54:57], v[126:129], v[166:169], v[54:57]
	v_mfma_f32_16x16x32_bf16 v[50:53], v[150:153], v[166:169], v[50:53]
	v_mfma_f32_16x16x32_bf16 v[34:37], v[150:153], v[174:177], v[34:37]
	v_mfma_f32_16x16x32_bf16 v[38:41], v[126:129], v[174:177], v[38:41]
	v_mfma_f32_16x16x32_bf16 v[22:25], v[126:129], v[182:185], v[22:25]
	v_mfma_f32_16x16x32_bf16 v[16:19], v[150:153], v[182:185], v[16:19]
	v_mfma_f32_16x16x32_bf16 v[0:3], v[150:153], v[202:205], v[0:3]
	v_mfma_f32_16x16x32_bf16 v[4:7], v[126:129], v[202:205], v[4:7]
	s_barrier
	s_setprio 0
	s_add_i32 s24, 0, 0x18000
	s_add_i32 s25, 0, 0x1c000
	v_add_u32_e32 v102, s24, v21
	v_add_u32_e32 v150, s25, v21
	ds_read_b128 v[66:69], v102
	ds_read_b128 v[78:81], v102 offset:1024
	ds_read_b128 v[90:93], v102 offset:2048
	ds_read_b128 v[102:105], v102 offset:3072
	ds_read_b128 v[114:117], v150
	ds_read_b128 v[126:129], v150 offset:1024
	ds_read_b128 v[138:141], v150 offset:2048
	ds_read_b128 v[150:153], v150 offset:3072
	s_add_u32 s8, s66, 0x160000
	s_addc_u32 s9, s67, 0
	s_mov_b32 m0, s37
	v_lshl_add_u64 v[218:219], s[8:9], 0, v[190:191]
	ds_read_b128 v[162:165], v228 offset:32768
	ds_read_b128 v[166:169], v228 offset:33792
	ds_read_b128 v[170:173], v228 offset:34816
	ds_read_b128 v[174:177], v228 offset:35840
	ds_read_b128 v[178:181], v228 offset:36864
	ds_read_b128 v[182:185], v228 offset:37888
	ds_read_b128 v[186:189], v228 offset:38912
	ds_read_b128 v[202:205], v228 offset:39936
	global_load_lds_dwordx4 v[218:219], off
	v_lshl_add_u64 v[218:219], s[8:9], 0, v[194:195]
	s_mov_b32 m0, s38
	s_nop 0
	global_load_lds_dwordx4 v[218:219], off
	s_waitcnt vmcnt(8)
	s_waitcnt lgkmcnt(0)
	s_setprio 1
	s_barrier
	v_mfma_f32_16x16x32_bf16 v[158:161], v[66:69], v[162:165], v[158:161]
	v_mfma_f32_16x16x32_bf16 v[154:157], v[90:93], v[162:165], v[154:157]
	v_mfma_f32_16x16x32_bf16 v[130:133], v[90:93], v[170:173], v[130:133]
	v_mfma_f32_16x16x32_bf16 v[134:137], v[66:69], v[170:173], v[134:137]
	v_mfma_f32_16x16x32_bf16 v[110:113], v[66:69], v[178:181], v[110:113]
	v_mfma_f32_16x16x32_bf16 v[106:109], v[90:93], v[178:181], v[106:109]
	v_mfma_f32_16x16x32_bf16 v[82:85], v[90:93], v[186:189], v[82:85]
	v_mfma_f32_16x16x32_bf16 v[86:89], v[66:69], v[186:189], v[86:89]
	v_mfma_f32_16x16x32_bf16 v[158:161], v[78:81], v[166:169], v[158:161]
	v_mfma_f32_16x16x32_bf16 v[154:157], v[102:105], v[166:169], v[154:157]
	v_mfma_f32_16x16x32_bf16 v[130:133], v[102:105], v[174:177], v[130:133]
	v_mfma_f32_16x16x32_bf16 v[134:137], v[78:81], v[174:177], v[134:137]
	v_mfma_f32_16x16x32_bf16 v[110:113], v[78:81], v[182:185], v[110:113]
	v_mfma_f32_16x16x32_bf16 v[106:109], v[102:105], v[182:185], v[106:109]
	v_mfma_f32_16x16x32_bf16 v[82:85], v[102:105], v[202:205], v[82:85]
	v_mfma_f32_16x16x32_bf16 v[86:89], v[78:81], v[202:205], v[86:89]
	v_mfma_f32_16x16x32_bf16 v[146:149], v[114:117], v[162:165], v[146:149]
	v_mfma_f32_16x16x32_bf16 v[142:145], v[138:141], v[162:165], v[142:145]
	v_mfma_f32_16x16x32_bf16 v[118:121], v[138:141], v[170:173], v[118:121]
	v_mfma_f32_16x16x32_bf16 v[122:125], v[114:117], v[170:173], v[122:125]
	v_mfma_f32_16x16x32_bf16 v[98:101], v[114:117], v[178:181], v[98:101]
	v_mfma_f32_16x16x32_bf16 v[94:97], v[138:141], v[178:181], v[94:97]
	v_mfma_f32_16x16x32_bf16 v[70:73], v[138:141], v[186:189], v[70:73]
	v_mfma_f32_16x16x32_bf16 v[74:77], v[114:117], v[186:189], v[74:77]
	v_mfma_f32_16x16x32_bf16 v[146:149], v[126:129], v[166:169], v[146:149]
	v_mfma_f32_16x16x32_bf16 v[142:145], v[150:153], v[166:169], v[142:145]
	v_mfma_f32_16x16x32_bf16 v[118:121], v[150:153], v[174:177], v[118:121]
	v_mfma_f32_16x16x32_bf16 v[122:125], v[126:129], v[174:177], v[122:125]
	v_mfma_f32_16x16x32_bf16 v[98:101], v[126:129], v[182:185], v[98:101]
	v_mfma_f32_16x16x32_bf16 v[94:97], v[150:153], v[182:185], v[94:97]
	v_mfma_f32_16x16x32_bf16 v[70:73], v[150:153], v[202:205], v[70:73]
	v_mfma_f32_16x16x32_bf16 v[74:77], v[126:129], v[202:205], v[74:77]
	s_barrier
; #define PG8_STAGE(bufoff, gbase, voff) do { _Pragma("unroll") for (int _i = 0; _i < 2; ++_i) \
;         __builtin_amdgcn_global_load_lds((const unsigned*)((const char*)(gbase) + (voff)[_i]), (PG8_LAS unsigned*)(lds + (bufoff) + ldsw + _i * 8192), 16, 0, 0); } while (0)
; #define PG8_LDA(dst, b, h) do { _Pragma("unroll") for (int m = 0; m < 4; ++m) _Pragma("unroll") for (int k = 0; k < 2; ++k) dst[m][k] = *(const PG8_LAS bf16x8*)(lds + PG8_SA(b, h) + aoff + m * 2048 + k * 1024); } while (0)
; #define PG8_MMA(ai, bj, At, Bt) do { __builtin_amdgcn_s_setprio(1); _Pragma("unroll") for (int m = 0; m < 4; ++m) _Pragma("unroll") for (int n = 0; n < 2; ++n) _Pragma("unroll") for (int k = 0; k < 2; ++k) \
;         acc[ai][bj][m][n] = __builtin_amdgcn_mfma_f32_16x16x32_bf16(Bt[n][k], At[m][k], acc[ai][bj][m][n], 0, 0, 0); __builtin_amdgcn_s_setprio(0); } while (0)
; #define PG8_WAIT_V(n) asm volatile("s_waitcnt vmcnt(" #n ")" ::: "memory")
; #define PG8_WAIT_L(n) asm volatile("s_waitcnt lgkmcnt(" #n ")" ::: "memory")
; #define PG8_BAR __builtin_amdgcn_s_barrier()
; #define PG8_SCHED __builtin_amdgcn_sched_barrier(0)
; template <class Epi, class Sched, bool ALIGN_EPI = false, bool SP2 = false>
; __device__ __forceinline__ void gemm_phase(PG8_LAS unsigned char* lds, const Gemm g, const Sched& S, const Epi& E, int tid_in) {
;     ...
;         for (int t = 0; t < nt; t += 2) {
;             const bool last = (t == nt - 2);
;             const char* a1 = cA + (size_t)(t + 1) * kstep;
;             const char* a2 = last ? nA : cA + (size_t)(t + 2) * kstep; const char* b2 = last ? nB : cB + (size_t)(t + 2) * kstep;
;     ...
;             PG8_LDA(At, 1, 1); PG8_STAGE(PG8_SB(1, 0), b3, voffB); PG8_STAGE(PG8_SB(1, 1), b3 + hstep, voffB); PG8_STAGE(PG8_SA(1, 0), a3, voffA);
;             PG8_WAIT_V(8); PG8_WAIT_L(0); PG8_BAR; PG8_MMA(1, 0, At, B0); PG8_MMA(1, 1, At, B1); PG8_BAR; PG8_SCHED;
	s_setprio 0
	s_add_i32 s8, s24, s14
	v_lshl_add_u64 v[206:207], v[206:207], 0, s[22:23]
	s_mov_b32 m0, s8
	ds_read_b128 v[162:165], v228 offset:49152
	ds_read_b128 v[166:169], v228 offset:50176
	ds_read_b128 v[170:173], v228 offset:51200
	ds_read_b128 v[174:177], v228 offset:52224
	ds_read_b128 v[178:181], v228 offset:53248
	ds_read_b128 v[182:185], v228 offset:54272
	ds_read_b128 v[186:189], v228 offset:55296
	ds_read_b128 v[202:205], v228 offset:56320
	global_load_lds_dwordx4 v[206:207], off
	s_add_i32 m0, s8, 0x2000
	s_add_u32 s8, s10, 0x160080
	v_lshl_add_u64 v[206:207], v[208:209], 0, s[22:23]
	s_addc_u32 s9, s11, 0
	s_add_i32 s10, s25, s14
	global_load_lds_dwordx4 v[206:207], off
	v_lshl_add_u64 v[206:207], s[8:9], 0, v[192:193]
	s_mov_b32 m0, s10
	s_nop 0
	global_load_lds_dwordx4 v[206:207], off
	v_lshl_add_u64 v[206:207], s[8:9], 0, v[196:197]
	s_add_i32 m0, s10, 0x2000
	s_nop 0
	global_load_lds_dwordx4 v[206:207], off
	v_lshl_add_u64 v[206:207], v[210:211], 0, s[22:23]
	s_mov_b32 m0, s71
	s_nop 0
	global_load_lds_dwordx4 v[206:207], off
	v_lshl_add_u64 v[206:207], v[212:213], 0, s[22:23]
	s_mov_b32 m0, s72
	s_nop 0
	global_load_lds_dwordx4 v[206:207], off
	s_waitcnt vmcnt(8)
	s_waitcnt lgkmcnt(0)
	s_setprio 1
	s_barrier
	v_mfma_f32_16x16x32_bf16 v[62:65], v[66:69], v[162:165], v[62:65]
	v_mfma_f32_16x16x32_bf16 v[58:61], v[90:93], v[162:165], v[58:61]
	v_mfma_f32_16x16x32_bf16 v[42:45], v[90:93], v[170:173], v[42:45]
	v_mfma_f32_16x16x32_bf16 v[46:49], v[66:69], v[170:173], v[46:49]
	v_mfma_f32_16x16x32_bf16 v[30:33], v[66:69], v[178:181], v[30:33]
	v_mfma_f32_16x16x32_bf16 v[26:29], v[90:93], v[178:181], v[26:29]
	v_mfma_f32_16x16x32_bf16 v[8:11], v[90:93], v[186:189], v[8:11]
	v_mfma_f32_16x16x32_bf16 v[12:15], v[66:69], v[186:189], v[12:15]
	v_mfma_f32_16x16x32_bf16 v[62:65], v[78:81], v[166:169], v[62:65]
	v_mfma_f32_16x16x32_bf16 v[58:61], v[102:105], v[166:169], v[58:61]
	v_mfma_f32_16x16x32_bf16 v[42:45], v[102:105], v[174:177], v[42:45]
	v_mfma_f32_16x16x32_bf16 v[46:49], v[78:81], v[174:177], v[46:49]
	v_mfma_f32_16x16x32_bf16 v[30:33], v[78:81], v[182:185], v[30:33]
	v_mfma_f32_16x16x32_bf16 v[26:29], v[102:105], v[182:185], v[26:29]
	v_mfma_f32_16x16x32_bf16 v[8:11], v[102:105], v[202:205], v[8:11]
	v_mfma_f32_16x16x32_bf16 v[12:15], v[78:81], v[202:205], v[12:15]
	v_mfma_f32_16x16x32_bf16 v[54:57], v[114:117], v[162:165], v[54:57]
	v_mfma_f32_16x16x32_bf16 v[50:53], v[138:141], v[162:165], v[50:53]
	v_mfma_f32_16x16x32_bf16 v[34:37], v[138:141], v[170:173], v[34:37]
	v_mfma_f32_16x16x32_bf16 v[38:41], v[114:117], v[170:173], v[38:41]
	v_mfma_f32_16x16x32_bf16 v[22:25], v[114:117], v[178:181], v[22:25]
	v_mfma_f32_16x16x32_bf16 v[16:19], v[138:141], v[178:181], v[16:19]
	v_mfma_f32_16x16x32_bf16 v[0:3], v[138:141], v[186:189], v[0:3]
	v_mfma_f32_16x16x32_bf16 v[4:7], v[114:117], v[186:189], v[4:7]
	v_mfma_f32_16x16x32_bf16 v[54:57], v[126:129], v[166:169], v[54:57]
	v_mfma_f32_16x16x32_bf16 v[50:53], v[150:153], v[166:169], v[50:53]
	v_mfma_f32_16x16x32_bf16 v[34:37], v[150:153], v[174:177], v[34:37]
	v_mfma_f32_16x16x32_bf16 v[38:41], v[126:129], v[174:177], v[38:41]
	v_mfma_f32_16x16x32_bf16 v[22:25], v[126:129], v[182:185], v[22:25]
	v_mfma_f32_16x16x32_bf16 v[16:19], v[150:153], v[182:185], v[16:19]
	v_mfma_f32_16x16x32_bf16 v[0:3], v[150:153], v[202:205], v[0:3]
	v_mfma_f32_16x16x32_bf16 v[4:7], v[126:129], v[202:205], v[4:7]
	s_barrier
	s_setprio 0
	s_add_i32 s79, s79, 2
	s_add_u32 s69, s69, 0x100
	s_addc_u32 s78, s78, 0
	s_cmpk_gt_u32 s79, 0x55
	s_mov_b64 s[8:9], s[6:7]
	s_cbranch_scc0 .LBB0_891
	s_and_b64 vcc, exec, s[56:57]
	s_cbranch_vccz .LBB0_894
	s_barrier
